# select key loads batched; DSA attention loop LDS fragment reads issued one group ahead
# speedup vs baseline: 1.0194x; 1.0105x over previous
; #define MFMA(a, b, c) __builtin_amdgcn_mfma_f32_32x32x16_bf16((a), (b), (c), 0, 0, 0)
; template <int MODE>
; DI void attn_item(const u16* Qp, int ldq, const u16* Kp, int ldk, const u16* VTp, int ldv, u16* Op, int ldo,
;                   int q0, int nkt, const float* Fc, const unsigned* BM, float kmaxn, char* smem) {
;     ...
;     for (int g4 = 0; g4 < 4; ++g4) {
;       const int k2 = g4 >> 1, s2 = g4 & 1;
;       const f32x16 zero16 = {0.f, 0.f, 0.f, 0.f, 0.f, 0.f, 0.f, 0.f, 0.f, 0.f, 0.f, 0.f, 0.f, 0.f, 0.f, 0.f};
; #pragma unroll
;       for (int st = s2 * 4; st < s2 * 4 + 4; ++st) {
;         bf16x8 a = *(const bf16x8*)(sKn + kro + k2 * 8192 + (((st * 2 + h) ^ ksw) << 4));
;         sn[k2] = (st == 0) ? MFMA(a, qf[st], zero16) : MFMA(a, qf[st], sn[k2]);
;       }
;       const unsigned wbits = k2 ? bw.y : bw.x;
;       float pv8[8];
; #pragma unroll
;       for (int e8 = 0; e8 < 8; ++e8) {
;         const int e = 8 * s2 + e8;
;         float pv;
;         if (MODE == 1) {
;           const float x = sc[k2][e];
;           pv = __builtin_amdgcn_exp2f(x - m_run);
;           if (diag) pv = (x <= -1e29f) ? 0.f : pv;
;         } else {
;           pv = __builtin_amdgcn_exp2f(sc[k2][e] * c1 - m_run);
;           if (MODE == 2) {
;             const int kb = 16 * ((e >> 2) >> 1) + 8 * h + 4 * ((e >> 2) & 1) + (e & 3);
;             const int msk = __builtin_amdgcn_sbfe(wbits, kb, 1);
;             pv = __int_as_float(__float_as_int(pv) & msk);
;           }
;         }
;         pv8[e8] = pv; ps += pv;
;       }
;       u32x4 u;
;       u[0] = pk2(pv8[0], pv8[1]); u[1] = pk2(pv8[2], pv8[3]); u[2] = pk2(pv8[4], pv8[5]); u[3] = pk2(pv8[6], pv8[7]);
;       const bf16x8 pfg = __builtin_bit_cast(bf16x8, u);
; #pragma unroll
;       for (int dt = 0; dt < 4; ++dt) {
;         bf16x8 a = *(const bf16x8*)(sV + vro + dt * 4096 + (((4 * k2 + 2 * s2 + h) ^ vsw) << 4));
;         o[dt] = MFMA(a, pfg, o[dt]);
;       }
;       __builtin_amdgcn_sched_barrier(0);
;     }
.LBB0_494:
	s_add_i32 s15, s14, 0xffff0000
	s_and_b32 s15, s15, 0x18000
	v_add_u32_e32 v252, s15, v172
	s_add_i32 s15, s14, 0xfffe8000
	s_and_b32 s15, s15, 0x18000
	v_add_u32_e32 v211, s15, v204
	v_add_u32_e32 v203, v252, v173
	v_add_u32_e32 v205, v252, v174
	v_add_u32_e32 v207, v252, v175
	v_add_u32_e32 v209, v252, v176
	v_add_u32_e32 v217, v211, v190
	ds_read_b128 v[224:227], v203
	ds_read_b128 v[228:231], v205
	ds_read_b128 v[232:235], v207
	ds_read_b128 v[236:239], v209
	ds_read_b128 v[240:243], v217 offset:16384
	ds_read_b128 v[244:247], v217 offset:20480
	ds_read_b128 v[248:251], v217 offset:24576
	ds_read_b128 v[212:215], v217 offset:28672
	v_fma_f32 v0, v96, s33, -v206
	v_fma_f32 v14, v97, s33, -v206
	v_fma_f32 v96, v98, s33, -v206
	v_fma_f32 v98, v99, s33, -v206
	s_waitcnt lgkmcnt(7)
	v_mfma_f32_32x32x16_bf16 v[112:127], v[224:227], v[128:131], 0
	v_add_u32_e32 v216, v252, v177
	ds_read_b128 v[224:227], v216
	v_fma_f32 v100, v100, s33, -v206
	v_exp_f32_e32 v14, v14
	v_exp_f32_e32 v98, v98
	v_fma_f32 v101, v101, s33, -v206
	v_exp_f32_e32 v96, v96
	s_waitcnt lgkmcnt(7)
	v_mfma_f32_32x32x16_bf16 v[112:127], v[228:231], v[132:135], v[112:127]
	v_add_u32_e32 v216, v252, v178
	ds_read_b128 v[228:231], v216
	v_bfe_i32 v15, v168, v183, 1
	v_bfe_i32 v99, v168, v185, 1
	v_exp_f32_e32 v208, v0
	v_and_b32_e32 v14, v15, v14
	s_waitcnt lgkmcnt(7)
	v_mfma_f32_32x32x16_bf16 v[112:127], v[232:235], v[136:139], v[112:127]
	v_add_u32_e32 v216, v252, v179
	ds_read_b128 v[232:235], v216
	v_exp_f32_e32 v4, v100
	v_exp_f32_e32 v5, v101
	v_bfe_i32 v6, v168, v186, 1
	v_and_b32_e32 v15, v99, v98
	v_and_b32_e32 v98, v6, v4
	v_fma_f32 v4, v102, s33, -v206
	v_bfe_i32 v97, v168, v184, 1
	s_waitcnt lgkmcnt(7)
	v_mfma_f32_32x32x16_bf16 v[112:127], v[236:239], v[140:143], v[112:127]
	v_add_u32_e32 v216, v252, v180
	ds_read_b128 v[236:239], v216
	v_bfe_i32 v7, v168, v187, 1
	v_exp_f32_e32 v8, v4
	v_fma_f32 v4, v103, s33, -v206
	v_and_b32_e32 v96, v97, v96
	v_and_b32_e32 v97, v7, v5
	v_exp_f32_e32 v9, v4
	v_bfe_i32 v13, v168, v170, 1
	v_bfe_i32 v10, v168, v188, 1
	v_bfe_i32 v11, v168, v189, 1
	v_and_b32_e32 v13, v13, v208
	v_and_b32_e32 v100, v11, v9
	v_and_b32_e32 v101, v10, v8
	v_cvt_pk_bf16_f32 v8, v13, v14
	v_cvt_pk_bf16_f32 v9, v96, v15
	v_cvt_pk_bf16_f32 v10, v98, v97
	v_cvt_pk_bf16_f32 v11, v101, v100
	v_add_u32_e32 v217, v211, v199
	s_waitcnt lgkmcnt(7)
	s_nop 0
	v_mfma_f32_32x32x16_bf16 v[64:79], v[240:243], v[8:11], v[64:79]
	ds_read_b128 v[240:243], v217 offset:16384
	s_waitcnt lgkmcnt(7)
	v_mfma_f32_32x32x16_bf16 v[48:63], v[244:247], v[8:11], v[48:63]
	ds_read_b128 v[244:247], v217 offset:20480
	s_waitcnt lgkmcnt(7)
	v_mfma_f32_32x32x16_bf16 v[32:47], v[248:251], v[8:11], v[32:47]
	ds_read_b128 v[248:251], v217 offset:24576
	s_waitcnt lgkmcnt(7)
	v_mfma_f32_32x32x16_bf16 v[16:31], v[212:215], v[8:11], v[16:31]
	ds_read_b128 v[212:215], v217 offset:28672
	v_add_f32_e32 v4, 0, v13
	v_add_f32_e32 v4, v4, v14
	v_add_f32_e32 v4, v4, v96
	v_add_f32_e32 v4, v4, v15
	v_add_f32_e32 v4, v4, v98
	v_add_f32_e32 v4, v4, v97
	v_add_f32_e32 v4, v4, v101
	v_add_f32_e32 v96, v4, v100
	s_waitcnt lgkmcnt(7)
	v_mfma_f32_32x32x16_bf16 v[112:127], v[224:227], v[144:147], v[112:127]
	ds_read_b128 v[224:227], v203 offset:8192
	s_waitcnt lgkmcnt(7)
	v_mfma_f32_32x32x16_bf16 v[112:127], v[228:231], v[148:151], v[112:127]
	ds_read_b128 v[228:231], v205 offset:8192
	s_waitcnt lgkmcnt(7)
	v_mfma_f32_32x32x16_bf16 v[112:127], v[232:235], v[152:155], v[112:127]
	ds_read_b128 v[232:235], v207 offset:8192
	s_waitcnt lgkmcnt(7)
	v_mfma_f32_32x32x16_bf16 v[112:127], v[236:239], v[156:159], v[112:127]
	ds_read_b128 v[236:239], v209 offset:8192
	v_fma_f32 v8, v104, s33, -v206
	v_fma_f32 v10, v105, s33, -v206
	v_exp_f32_e32 v8, v8
	v_exp_f32_e32 v10, v10
	v_bfe_i32 v9, v168, v191, 1
	v_bfe_i32 v11, v168, v192, 1
	v_and_b32_e32 v98, v9, v8
	v_and_b32_e32 v97, v11, v10
	v_fma_f32 v8, v106, s33, -v206
	v_fma_f32 v10, v107, s33, -v206
	v_exp_f32_e32 v8, v8
	v_exp_f32_e32 v10, v10
	v_bfe_i32 v9, v168, v193, 1
	v_bfe_i32 v11, v168, v194, 1
	v_and_b32_e32 v100, v9, v8
	v_and_b32_e32 v99, v11, v10
	v_fma_f32 v8, v108, s33, -v206
	v_fma_f32 v10, v109, s33, -v206
	v_exp_f32_e32 v8, v8
	v_exp_f32_e32 v10, v10
	v_bfe_i32 v9, v168, v195, 1
	v_bfe_i32 v11, v168, v196, 1
	v_and_b32_e32 v101, v11, v10
	v_and_b32_e32 v102, v9, v8
	v_fma_f32 v8, v110, s33, -v206
	v_fma_f32 v10, v111, s33, -v206
	v_exp_f32_e32 v8, v8
	v_exp_f32_e32 v10, v10
	v_bfe_i32 v9, v168, v197, 1
	v_bfe_i32 v11, v168, v198, 1
	v_and_b32_e32 v104, v9, v8
	v_and_b32_e32 v103, v11, v10
	v_cvt_pk_bf16_f32 v8, v98, v97
	v_cvt_pk_bf16_f32 v9, v100, v99
	v_cvt_pk_bf16_f32 v10, v102, v101
	v_cvt_pk_bf16_f32 v11, v104, v103
	v_add_u32_e32 v217, v211, v200
	s_waitcnt lgkmcnt(7)
	s_nop 0
	v_mfma_f32_32x32x16_bf16 v[64:79], v[240:243], v[8:11], v[64:79]
	ds_read_b128 v[240:243], v217 offset:16384
	s_waitcnt lgkmcnt(7)
	v_mfma_f32_32x32x16_bf16 v[48:63], v[244:247], v[8:11], v[48:63]
	ds_read_b128 v[244:247], v217 offset:20480
	s_waitcnt lgkmcnt(7)
	v_mfma_f32_32x32x16_bf16 v[32:47], v[248:251], v[8:11], v[32:47]
	ds_read_b128 v[248:251], v217 offset:24576
	s_waitcnt lgkmcnt(7)
	v_mfma_f32_32x32x16_bf16 v[16:31], v[212:215], v[8:11], v[16:31]
	ds_read_b128 v[212:215], v217 offset:28672
	v_add_f32_e32 v8, v96, v98
	v_add_f32_e32 v8, v8, v97
	v_add_f32_e32 v8, v8, v100
	v_add_f32_e32 v8, v8, v99
	v_add_f32_e32 v8, v8, v102
	v_add_f32_e32 v8, v8, v101
	v_add_f32_e32 v8, v8, v104
	v_add_f32_e32 v168, v8, v103
	s_waitcnt lgkmcnt(7)
; template <int MODE>
; DI void attn_item(const u16* Qp, int ldq, const u16* Kp, int ldk, const u16* VTp, int ldv, u16* Op, int ldo,
;                   int q0, int nkt, const float* Fc, const unsigned* BM, float kmaxn, char* smem) {
;     ...
;     for (int g4 = 0; g4 < 4; ++g4) {
;       const int k2 = g4 >> 1, s2 = g4 & 1;
;       const f32x16 zero16 = {0.f, 0.f, 0.f, 0.f, 0.f, 0.f, 0.f, 0.f, 0.f, 0.f, 0.f, 0.f, 0.f, 0.f, 0.f, 0.f};
; #pragma unroll
;       for (int st = s2 * 4; st < s2 * 4 + 4; ++st) {
;         bf16x8 a = *(const bf16x8*)(sKn + kro + k2 * 8192 + (((st * 2 + h) ^ ksw) << 4));
;         sn[k2] = (st == 0) ? MFMA(a, qf[st], zero16) : MFMA(a, qf[st], sn[k2]);
;       }
;       const unsigned wbits = k2 ? bw.y : bw.x;
;       float pv8[8];
; #pragma unroll
;       for (int e8 = 0; e8 < 8; ++e8) {
;         const int e = 8 * s2 + e8;
;         float pv;
;         if (MODE == 1) {
;           const float x = sc[k2][e];
;           pv = __builtin_amdgcn_exp2f(x - m_run);
;           if (diag) pv = (x <= -1e29f) ? 0.f : pv;
;         } else {
;           pv = __builtin_amdgcn_exp2f(sc[k2][e] * c1 - m_run);
;           if (MODE == 2) {
;             const int kb = 16 * ((e >> 2) >> 1) + 8 * h + 4 * ((e >> 2) & 1) + (e & 3);
;             const int msk = __builtin_amdgcn_sbfe(wbits, kb, 1);
;             pv = __int_as_float(__float_as_int(pv) & msk);
;           }
;         }
;         pv8[e8] = pv; ps += pv;
;       }
;       u32x4 u;
;       u[0] = pk2(pv8[0], pv8[1]); u[1] = pk2(pv8[2], pv8[3]); u[2] = pk2(pv8[4], pv8[5]); u[3] = pk2(pv8[6], pv8[7]);
;       const bf16x8 pfg = __builtin_bit_cast(bf16x8, u);
; #pragma unroll
;       for (int dt = 0; dt < 4; ++dt) {
;         bf16x8 a = *(const bf16x8*)(sV + vro + dt * 4096 + (((4 * k2 + 2 * s2 + h) ^ vsw) << 4));
;         o[dt] = MFMA(a, pfg, o[dt]);
;       }
;       __builtin_amdgcn_sched_barrier(0);
;     }
;     l_run += ps;
;     asm volatile("s_waitcnt vmcnt(4)" ::: "memory");
;     if (MODE == 1 && tid < 16) *(f32x4*)(fct + ((kt + 1) & 3) * 64 + tid * 4) = rf;
;     if (MODE == 1) {
;       const int v = __all((qkb - flast) < (m_run - 160.f)) ? 1 : 0;
;       if (lane == 0) votes[(kt & 1) * 8 + wave] = v;
;     }
;     asm volatile("s_waitcnt lgkmcnt(0)" ::: "memory");
;     __builtin_amdgcn_s_barrier();
;     asm volatile("" ::: "memory");
;     sc[0] = sn[0]; sc[1] = sn[1]; bw = bwn;
	v_mfma_f32_32x32x16_bf16 v[96:111], v[224:227], v[128:131], 0
	v_add_u32_e32 v216, v252, v177
	ds_read_b128 v[224:227], v216 offset:8192
	s_waitcnt lgkmcnt(7)
	v_mfma_f32_32x32x16_bf16 v[96:111], v[228:231], v[132:135], v[96:111]
	v_add_u32_e32 v216, v252, v178
	ds_read_b128 v[228:231], v216 offset:8192
	s_waitcnt lgkmcnt(7)
	v_mfma_f32_32x32x16_bf16 v[96:111], v[232:235], v[136:139], v[96:111]
	v_add_u32_e32 v216, v252, v179
	ds_read_b128 v[232:235], v216 offset:8192
	s_waitcnt lgkmcnt(7)
	v_mfma_f32_32x32x16_bf16 v[96:111], v[236:239], v[140:143], v[96:111]
	v_add_u32_e32 v216, v252, v180
	ds_read_b128 v[236:239], v216 offset:8192
	v_fma_f32 v8, v80, s33, -v206
	v_fma_f32 v10, v81, s33, -v206
	v_exp_f32_e32 v8, v8
	v_exp_f32_e32 v10, v10
	v_bfe_i32 v9, v169, v170, 1
	v_bfe_i32 v11, v169, v183, 1
	v_and_b32_e32 v81, v9, v8
	v_and_b32_e32 v80, v11, v10
	v_fma_f32 v8, v82, s33, -v206
	v_fma_f32 v10, v83, s33, -v206
	v_exp_f32_e32 v8, v8
	v_exp_f32_e32 v10, v10
	v_bfe_i32 v9, v169, v184, 1
	v_bfe_i32 v11, v169, v185, 1
	v_and_b32_e32 v83, v9, v8
	v_and_b32_e32 v82, v11, v10
	v_fma_f32 v8, v84, s33, -v206
	v_fma_f32 v10, v85, s33, -v206
	v_exp_f32_e32 v8, v8
	v_exp_f32_e32 v10, v10
	v_bfe_i32 v9, v169, v186, 1
	v_bfe_i32 v11, v169, v187, 1
	v_and_b32_e32 v85, v9, v8
	v_and_b32_e32 v84, v11, v10
	v_fma_f32 v8, v86, s33, -v206
	v_fma_f32 v10, v87, s33, -v206
	v_exp_f32_e32 v8, v8
	v_exp_f32_e32 v10, v10
	v_bfe_i32 v9, v169, v188, 1
	v_bfe_i32 v11, v169, v189, 1
	v_and_b32_e32 v87, v9, v8
	v_and_b32_e32 v86, v11, v10
	v_cvt_pk_bf16_f32 v8, v81, v80
	v_cvt_pk_bf16_f32 v9, v83, v82
	v_cvt_pk_bf16_f32 v10, v85, v84
	v_cvt_pk_bf16_f32 v11, v87, v86
	v_add_u32_e32 v217, v211, v202
	s_waitcnt lgkmcnt(7)
	s_nop 0
	v_mfma_f32_32x32x16_bf16 v[64:79], v[240:243], v[8:11], v[64:79]
	ds_read_b128 v[240:243], v217 offset:16384
	s_waitcnt lgkmcnt(7)
	v_mfma_f32_32x32x16_bf16 v[48:63], v[244:247], v[8:11], v[48:63]
	ds_read_b128 v[244:247], v217 offset:20480
	s_waitcnt lgkmcnt(7)
	v_mfma_f32_32x32x16_bf16 v[32:47], v[248:251], v[8:11], v[32:47]
	ds_read_b128 v[248:251], v217 offset:24576
	s_waitcnt lgkmcnt(7)
	v_mfma_f32_32x32x16_bf16 v[16:31], v[212:215], v[8:11], v[16:31]
	ds_read_b128 v[212:215], v217 offset:28672
	v_add_f32_e32 v8, v168, v81
	v_add_f32_e32 v8, v8, v80
	v_add_f32_e32 v8, v8, v83
	v_add_f32_e32 v8, v8, v82
	v_add_f32_e32 v8, v8, v85
	v_add_f32_e32 v8, v8, v84
	v_add_f32_e32 v8, v8, v87
	v_add_f32_e32 v12, v8, v86
	s_waitcnt lgkmcnt(7)
	v_mfma_f32_32x32x16_bf16 v[96:111], v[224:227], v[144:147], v[96:111]
	s_waitcnt lgkmcnt(6)
	v_mfma_f32_32x32x16_bf16 v[96:111], v[228:231], v[148:151], v[96:111]
	s_waitcnt lgkmcnt(5)
	v_mfma_f32_32x32x16_bf16 v[96:111], v[232:235], v[152:155], v[96:111]
	s_waitcnt lgkmcnt(4)
	v_mfma_f32_32x32x16_bf16 v[96:111], v[236:239], v[156:159], v[96:111]
	v_fma_f32 v4, v88, s33, -v206
	v_fma_f32 v6, v89, s33, -v206
	v_exp_f32_e32 v4, v4
	v_exp_f32_e32 v6, v6
	v_bfe_i32 v5, v169, v191, 1
	v_bfe_i32 v7, v169, v192, 1
	v_and_b32_e32 v14, v5, v4
	v_and_b32_e32 v13, v7, v6
	v_fma_f32 v4, v90, s33, -v206
	v_fma_f32 v6, v91, s33, -v206
	v_exp_f32_e32 v4, v4
	v_exp_f32_e32 v6, v6
	v_bfe_i32 v5, v169, v193, 1
	v_bfe_i32 v7, v169, v194, 1
	v_and_b32_e32 v80, v5, v4
	v_and_b32_e32 v15, v7, v6
	v_fma_f32 v4, v92, s33, -v206
	v_fma_f32 v6, v93, s33, -v206
	v_exp_f32_e32 v4, v4
	v_exp_f32_e32 v6, v6
	v_bfe_i32 v5, v169, v195, 1
	v_bfe_i32 v7, v169, v196, 1
	v_and_b32_e32 v82, v5, v4
	v_and_b32_e32 v81, v7, v6
	v_fma_f32 v4, v94, s33, -v206
	v_fma_f32 v6, v95, s33, -v206
	v_exp_f32_e32 v4, v4
	v_exp_f32_e32 v6, v6
	v_bfe_i32 v5, v169, v197, 1
	v_bfe_i32 v7, v169, v198, 1
	v_and_b32_e32 v84, v5, v4
	v_and_b32_e32 v83, v7, v6
	v_cvt_pk_bf16_f32 v4, v14, v13
	v_cvt_pk_bf16_f32 v5, v80, v15
	v_cvt_pk_bf16_f32 v6, v82, v81
	v_cvt_pk_bf16_f32 v7, v84, v83
	s_waitcnt lgkmcnt(3)
	s_nop 0
	v_mfma_f32_32x32x16_bf16 v[64:79], v[240:243], v[4:7], v[64:79]
	s_waitcnt lgkmcnt(2)
	v_mfma_f32_32x32x16_bf16 v[48:63], v[244:247], v[4:7], v[48:63]
	s_waitcnt lgkmcnt(1)
	v_mfma_f32_32x32x16_bf16 v[32:47], v[248:251], v[4:7], v[32:47]
	v_add_f32_e32 v0, v12, v14
	v_add_f32_e32 v0, v0, v13
	v_add_f32_e32 v0, v0, v80
	v_add_f32_e32 v0, v0, v15
	v_add_f32_e32 v0, v0, v82
	v_add_f32_e32 v0, v0, v81
	s_waitcnt lgkmcnt(0)
	v_mfma_f32_32x32x16_bf16 v[16:31], v[212:215], v[4:7], v[16:31]
	v_add_f32_e32 v0, v0, v84
	v_add_f32_e32 v0, v0, v83
	s_waitcnt vmcnt(4)
	s_waitcnt lgkmcnt(0)
	s_barrier
	s_add_i32 s14, s14, 0x8000
	v_add_f32_e32 v182, v182, v0
	s_cmp_lg_u32 s12, s13
	s_cbranch_scc0 .LBB0_489
	v_mov_b64_e32 v[80:81], v[96:97]
	v_mov_b64_e32 v[82:83], v[98:99]
	v_mov_b64_e32 v[84:85], v[100:101]
	v_mov_b64_e32 v[86:87], v[102:103]
	v_mov_b64_e32 v[88:89], v[104:105]
	v_mov_b64_e32 v[90:91], v[106:107]
	v_mov_b64_e32 v[92:93], v[108:109]
	v_mov_b64_e32 v[94:95], v[110:111]
	v_mov_b64_e32 v[96:97], v[112:113]
	v_mov_b64_e32 v[98:99], v[114:115]
	v_mov_b64_e32 v[100:101], v[116:117]
	v_mov_b64_e32 v[102:103], v[118:119]
	v_mov_b64_e32 v[104:105], v[120:121]
	v_mov_b64_e32 v[106:107], v[122:123]
	v_mov_b64_e32 v[108:109], v[124:125]
	v_mov_b64_e32 v[110:111], v[126:127]
	s_waitcnt vmcnt(0)
	v_mov_b64_e32 v[168:169], v[2:3]
	s_branch .LBB0_492

; template <int NJ>
; DI void select_row(const float* row, int n, u64* bmrow, int lane) {
;     ...
;   for (int jj = 0; jj < NJ; ++jj) {
;     const int idx = jj * 64 + lane;
;     unsigned k = 0;
;     if (idx < n) { unsigned u = __float_as_uint(__builtin_nontemporal_load(row + idx)); k = (u & 0x80000000u) ? ~u : (u | 0x80000000u); }
;     key[jj] = k;
;   }
; DI void select_phase(const Params& p) {
;     ...
;     const int rowi = base + ((it & 1) ? (nw - 1 - gw) : gw);
;     if (rowi >= NTOK) continue;
;     const int b = rowi >> 13, t = rowi & 8191, blk = t >> 6, rr = t & 63, n = (blk + 1) * 64;
;     const float* row = SC + (size_t)b * SCB + (size_t)2048 * blk * (blk + 1) + (size_t)rr * n;
;     u64* bmrow = BM + (size_t)rowi * 128;
;     if (n <= 256) {
;       const int nwd = n >> 6;
;       bmrow[lane] = (lane < nwd) ? ~0ull : 0ull; bmrow[64 + lane] = 0ull;
;     } else if (n <= 2048) select_row<32>(row, n, bmrow, lane);
;     else if (n <= 4096) select_row<64>(row, n, bmrow, lane);
;     else select_row<128>(row, n, bmrow, lane);
;   }
.LBB0_502:
	s_bitcmp0_b32 s36, 0
	s_cselect_b64 vcc, -1, 0
	v_xad_u32 v0, v3, -1, s6
	v_cndmask_b32_e32 v0, v0, v3, vcc
	v_add_u32_e32 v230, s46, v0
	s_movk_i32 s6, 0x4000
	v_cmp_gt_i32_e32 vcc, s6, v230
	s_and_saveexec_b64 s[12:13], vcc
	s_cbranch_execz .LBB0_501
	v_ashrrev_i32_e32 v231, 31, v230
	v_bfe_u32 v4, v230, 6, 7
	v_lshlrev_b64 v[16:17], 10, v[230:231]
	v_lshl_add_u64 v[228:229], s[10:11], 0, v[16:17]
	v_cmp_lt_u32_e32 vcc, 3, v4
	s_and_saveexec_b64 s[6:7], vcc
	s_xor_b64 s[14:15], exec, s[6:7]
	s_cbranch_execz .LBB0_802
	v_ashrrev_i32_e32 v0, 13, v230
	v_mov_b64_e32 v[16:17], s[8:9]
	s_mov_b32 s6, 0x8100000
	v_add_u32_e32 v8, 1, v4
	v_mad_i64_i32 v[16:17], s[6:7], v0, s6, v[16:17]
	v_lshlrev_b32_e32 v0, 11, v4
	v_mul_u32_u24_e32 v0, v0, v8
	v_and_b32_e32 v6, 63, v230
	v_lshlrev_b32_e32 v244, 6, v8
	v_lshlrev_b32_e32 v0, 2, v0
	v_lshl_add_u64 v[16:17], v[16:17], 0, v[0:1]
	v_mul_u32_u24_e32 v0, v244, v6
	v_lshlrev_b32_e32 v0, 2, v0
	v_lshl_add_u64 v[230:231], v[16:17], 0, v[0:1]
	v_cmp_lt_u32_e32 vcc, 31, v4
	v_lshlrev_b32_e32 v0, 2, v2
	s_and_saveexec_b64 s[6:7], vcc
	s_xor_b64 s[16:17], exec, s[6:7]
	s_cbranch_execz .LBB0_726
	v_lshl_add_u64 v[234:235], v[230:231], 0, v[0:1]
	global_load_dword v0, v[234:235], off nt
	global_load_dword v6, v[234:235], off offset:256 nt
	global_load_dword v8, v[234:235], off offset:512 nt
	global_load_dword v10, v[234:235], off offset:768 nt
	global_load_dword v12, v[234:235], off offset:1024 nt
	global_load_dword v14, v[234:235], off offset:1280 nt
	global_load_dword v18, v[234:235], off offset:1536 nt
	global_load_dword v19, v[234:235], off offset:1792 nt
	global_load_dword v20, v[234:235], off offset:2048 nt
	global_load_dword v21, v[234:235], off offset:2304 nt
	global_load_dword v22, v[234:235], off offset:2560 nt
	global_load_dword v23, v[234:235], off offset:2816 nt
	global_load_dword v24, v[234:235], off offset:3072 nt
	global_load_dword v25, v[234:235], off offset:3328 nt
	global_load_dword v26, v[234:235], off offset:3584 nt
	global_load_dword v27, v[234:235], off offset:3840 nt
	s_movk_i32 s6, 0x1000
	v_add_co_u32_e32 v16, vcc, s6, v234
	s_waitcnt vmcnt(0)
	v_cmp_gt_i32_e64 s[6:7], 0, v0
	v_addc_co_u32_e32 v17, vcc, 0, v235, vcc
	global_load_dword v28, v[16:17], off nt
	global_load_dword v29, v[16:17], off offset:256 nt
	global_load_dword v30, v[16:17], off offset:512 nt
	global_load_dword v31, v[16:17], off offset:768 nt
	global_load_dword v32, v[16:17], off offset:1024 nt
	global_load_dword v33, v[16:17], off offset:1280 nt
	global_load_dword v34, v[16:17], off offset:1536 nt
	global_load_dword v36, v[16:17], off offset:1792 nt
	v_cmp_lt_u32_e32 vcc, 63, v4
	global_load_dword v4, v[16:17], off offset:2048 nt
	global_load_dword v38, v[16:17], off offset:2304 nt
	global_load_dword v40, v[16:17], off offset:2560 nt
	global_load_dword v81, v[16:17], off offset:2816 nt
	global_load_dword v83, v[16:17], off offset:3072 nt
	global_load_dword v85, v[16:17], off offset:3328 nt
	global_load_dword v87, v[16:17], off offset:3584 nt
	s_nop 0
	global_load_dword v16, v[16:17], off offset:3840 nt
	v_not_b32_e32 v17, v0
	v_not_b32_e32 v35, v6
	v_cndmask_b32_e64 v79, -|v0|, v17, s[6:7]
	v_cmp_gt_i32_e64 s[6:7], 0, v6
	v_not_b32_e32 v37, v8
	v_not_b32_e32 v39, v10
	v_cndmask_b32_e64 v77, -|v6|, v35, s[6:7]
	v_cmp_gt_i32_e64 s[6:7], 0, v8
	v_not_b32_e32 v41, v12
	v_not_b32_e32 v43, v14
	v_cndmask_b32_e64 v75, -|v8|, v37, s[6:7]
	v_cmp_gt_i32_e64 s[6:7], 0, v10
	v_not_b32_e32 v45, v18
	v_not_b32_e32 v47, v19
	v_cndmask_b32_e64 v73, -|v10|, v39, s[6:7]
	v_cmp_gt_i32_e64 s[6:7], 0, v12
	v_not_b32_e32 v49, v20
	v_not_b32_e32 v51, v21
	v_cndmask_b32_e64 v71, -|v12|, v41, s[6:7]
	v_cmp_gt_i32_e64 s[6:7], 0, v14
	v_not_b32_e32 v53, v22
	v_not_b32_e32 v55, v23
	v_cndmask_b32_e64 v69, -|v14|, v43, s[6:7]
	v_cmp_gt_i32_e64 s[6:7], 0, v18
	v_not_b32_e32 v89, v24
	v_not_b32_e32 v91, v25
	v_cndmask_b32_e64 v67, -|v18|, v45, s[6:7]
	v_cmp_gt_i32_e64 s[6:7], 0, v19
	v_not_b32_e32 v93, v26
	v_not_b32_e32 v0, v27
	v_cndmask_b32_e64 v65, -|v19|, v47, s[6:7]
	v_cmp_gt_i32_e64 s[6:7], 0, v20
	s_nop 1
	v_cndmask_b32_e64 v63, -|v20|, v49, s[6:7]
	v_cmp_gt_i32_e64 s[6:7], 0, v21
	s_nop 1
	v_cndmask_b32_e64 v61, -|v21|, v51, s[6:7]
	v_cmp_gt_i32_e64 s[6:7], 0, v22
	s_nop 1
	v_cndmask_b32_e64 v59, -|v22|, v53, s[6:7]
	v_cmp_gt_i32_e64 s[6:7], 0, v23
	s_nop 1
	v_cndmask_b32_e64 v57, -|v23|, v55, s[6:7]
	v_cmp_gt_i32_e64 s[6:7], 0, v24
	s_nop 1
	v_cndmask_b32_e64 v55, -|v24|, v89, s[6:7]
	v_cmp_gt_i32_e64 s[6:7], 0, v25
	s_nop 1
	v_cndmask_b32_e64 v51, -|v25|, v91, s[6:7]
	v_cmp_gt_i32_e64 s[6:7], 0, v26
	s_nop 1
	v_cndmask_b32_e64 v53, -|v26|, v93, s[6:7]
	v_cmp_gt_i32_e64 s[6:7], 0, v27
	s_nop 1
	v_cndmask_b32_e64 v49, -|v27|, v0, s[6:7]
	s_waitcnt vmcnt(15)
	v_not_b32_e32 v0, v28
	v_cmp_gt_i32_e64 s[6:7], 0, v28
	s_nop 1
	v_cndmask_b32_e64 v47, -|v28|, v0, s[6:7]
	s_waitcnt vmcnt(14)
	v_not_b32_e32 v0, v29
	v_cmp_gt_i32_e64 s[6:7], 0, v29
	s_nop 1
	v_cndmask_b32_e64 v45, -|v29|, v0, s[6:7]
	s_waitcnt vmcnt(13)
	v_not_b32_e32 v0, v30
	v_cmp_gt_i32_e64 s[6:7], 0, v30
	s_nop 1
	v_cndmask_b32_e64 v43, -|v30|, v0, s[6:7]
	s_waitcnt vmcnt(12)
	v_not_b32_e32 v0, v31
	v_cmp_gt_i32_e64 s[6:7], 0, v31
	s_nop 1
	v_cndmask_b32_e64 v41, -|v31|, v0, s[6:7]
	s_waitcnt vmcnt(11)
	v_not_b32_e32 v0, v32
	v_cmp_gt_i32_e64 s[6:7], 0, v32
	s_nop 1
	v_cndmask_b32_e64 v39, -|v32|, v0, s[6:7]
	s_waitcnt vmcnt(10)
	v_not_b32_e32 v0, v33
	v_cmp_gt_i32_e64 s[6:7], 0, v33
	s_nop 1
	v_cndmask_b32_e64 v37, -|v33|, v0, s[6:7]
	s_waitcnt vmcnt(9)
	v_not_b32_e32 v0, v34
	v_cmp_gt_i32_e64 s[6:7], 0, v34
	s_nop 1
	v_cndmask_b32_e64 v35, -|v34|, v0, s[6:7]
	s_waitcnt vmcnt(8)
	v_not_b32_e32 v0, v36
	v_cmp_gt_i32_e64 s[6:7], 0, v36
	s_nop 1
	v_cndmask_b32_e64 v33, -|v36|, v0, s[6:7]
	s_waitcnt vmcnt(7)
	v_not_b32_e32 v0, v4
	v_cmp_gt_i32_e64 s[6:7], 0, v4
	s_nop 1
	v_cndmask_b32_e64 v31, -|v4|, v0, s[6:7]
	s_waitcnt vmcnt(6)
	v_not_b32_e32 v0, v38
	v_cmp_gt_i32_e64 s[6:7], 0, v38
	s_nop 1
	v_cndmask_b32_e64 v29, -|v38|, v0, s[6:7]
	s_waitcnt vmcnt(5)
	v_not_b32_e32 v0, v40
	v_cmp_gt_i32_e64 s[6:7], 0, v40
	s_nop 1
	v_cndmask_b32_e64 v27, -|v40|, v0, s[6:7]
	s_waitcnt vmcnt(4)
	v_not_b32_e32 v0, v81
	v_cmp_gt_i32_e64 s[6:7], 0, v81
	s_nop 1
	v_cndmask_b32_e64 v25, -|v81|, v0, s[6:7]
	s_waitcnt vmcnt(3)
	v_not_b32_e32 v0, v83
	v_cmp_gt_i32_e64 s[6:7], 0, v83
	s_nop 1
	v_cndmask_b32_e64 v23, -|v83|, v0, s[6:7]
	s_waitcnt vmcnt(2)
	v_not_b32_e32 v0, v85
	v_cmp_gt_i32_e64 s[6:7], 0, v85
	s_nop 1
	v_cndmask_b32_e64 v21, -|v85|, v0, s[6:7]
	s_waitcnt vmcnt(1)
	v_not_b32_e32 v0, v87
	v_cmp_gt_i32_e64 s[6:7], 0, v87
	s_nop 1
	v_cndmask_b32_e64 v19, -|v87|, v0, s[6:7]
	s_waitcnt vmcnt(0)
	v_not_b32_e32 v0, v16
	v_cmp_gt_i32_e64 s[6:7], 0, v16
	s_nop 1
	v_cndmask_b32_e64 v17, -|v16|, v0, s[6:7]
	s_and_saveexec_b64 s[6:7], vcc
	s_xor_b64 s[18:19], exec, s[6:7]
	s_cbranch_execz .LBB0_652
; template <int NJ>
; DI void select_row(const float* row, int n, u64* bmrow, int lane) {
;     ...
;   for (int jj = 0; jj < NJ; ++jj) {
;     const int idx = jj * 64 + lane;
;     unsigned k = 0;
;     if (idx < n) { unsigned u = __float_as_uint(__builtin_nontemporal_load(row + idx)); k = (u & 0x80000000u) ? ~u : (u | 0x80000000u); }
;     key[jj] = k;
;   }
	v_add_co_u32_e32 v212, vcc, 0x2000, v234
	s_movk_i32 s6, 0x3000
	s_nop 0
	v_addc_co_u32_e32 v213, vcc, 0, v235, vcc
	global_load_dword v30, v[212:213], off nt
	global_load_dword v28, v[212:213], off offset:256 nt
	global_load_dword v26, v[212:213], off offset:512 nt
	global_load_dword v24, v[212:213], off offset:768 nt
	global_load_dword v22, v[212:213], off offset:1024 nt
	global_load_dword v20, v[212:213], off offset:1280 nt
	global_load_dword v18, v[212:213], off offset:1536 nt
	global_load_dword v16, v[212:213], off offset:1792 nt
	global_load_dword v14, v[212:213], off offset:2048 nt
	global_load_dword v12, v[212:213], off offset:2304 nt
	global_load_dword v10, v[212:213], off offset:2560 nt
	global_load_dword v8, v[212:213], off offset:2816 nt
	global_load_dword v6, v[212:213], off offset:3072 nt
	global_load_dword v4, v[212:213], off offset:3328 nt
	global_load_dword v236, v[212:213], off offset:3584 nt
	global_load_dword v211, v[212:213], off offset:3840 nt
	v_add_co_u32_e32 v212, vcc, s6, v234
	v_mov_b32_e32 v81, 0
	s_nop 0
	v_addc_co_u32_e32 v213, vcc, 0, v235, vcc
	global_load_dword v36, v[212:213], off nt
	global_load_dword v239, v[212:213], off offset:256 nt
	global_load_dword v227, v[212:213], off offset:512 nt
	global_load_dword v253, v[212:213], off offset:768 nt
	global_load_dword v252, v[212:213], off offset:1024 nt
	global_load_dword v251, v[212:213], off offset:1280 nt
	global_load_dword v250, v[212:213], off offset:1536 nt
	global_load_dword v249, v[212:213], off offset:1792 nt
	global_load_dword v248, v[212:213], off offset:2048 nt
	global_load_dword v247, v[212:213], off offset:2304 nt
	global_load_dword v246, v[212:213], off offset:2560 nt
	global_load_dword v245, v[212:213], off offset:2816 nt
	global_load_dword v233, v[212:213], off offset:3072 nt
	global_load_dword v232, v[212:213], off offset:3328 nt
	global_load_dword v34, v[212:213], off offset:3584 nt
	global_load_dword v32, v[212:213], off offset:3840 nt
	v_cmp_lt_u32_e32 vcc, v214, v244
	v_mov_b32_e32 v83, 0
	s_and_saveexec_b64 s[6:7], vcc
	s_cbranch_execz .LBB0_508
	v_lshlrev_b32_e32 v0, 2, v214
	v_lshl_add_u64 v[212:213], v[230:231], 0, v[0:1]
	global_load_dword v83, v[212:213], off nt
.LBB0_508:
	s_or_b64 exec, exec, s[6:7]
	v_cmp_lt_u32_e32 vcc, v216, v244
	s_and_saveexec_b64 s[6:7], vcc
	s_cbranch_execz .LBB0_510
	v_lshlrev_b32_e32 v0, 2, v216
	v_lshl_add_u64 v[212:213], v[230:231], 0, v[0:1]
	global_load_dword v81, v[212:213], off nt
.LBB0_510:
	s_or_b64 exec, exec, s[6:7]
	v_cmp_lt_u32_e32 vcc, v224, v244
	v_mov_b32_e32 v85, 0
	v_mov_b32_e32 v87, 0
	s_and_saveexec_b64 s[6:7], vcc
	s_cbranch_execz .LBB0_512
	v_lshlrev_b32_e32 v0, 2, v224
	v_lshl_add_u64 v[212:213], v[230:231], 0, v[0:1]
	global_load_dword v87, v[212:213], off nt
.LBB0_512:
	s_or_b64 exec, exec, s[6:7]
	v_or_b32_e32 v0, 0x10c0, v2
	v_cmp_lt_u32_e32 vcc, v0, v244
	s_and_saveexec_b64 s[6:7], vcc
	s_cbranch_execz .LBB0_514
	v_or_b32_e32 v0, 0x10c0, v2
	v_lshlrev_b32_e32 v0, 2, v0
	v_lshl_add_u64 v[212:213], v[230:231], 0, v[0:1]
	global_load_dword v85, v[212:213], off nt
.LBB0_514:
	s_or_b64 exec, exec, s[6:7]
	v_or_b32_e32 v0, 0x1100, v2
	v_cmp_lt_u32_e32 vcc, v0, v244
	v_mov_b32_e32 v89, 0
	v_mov_b32_e32 v91, 0
	s_and_saveexec_b64 s[6:7], vcc
	s_cbranch_execz .LBB0_516
	v_or_b32_e32 v0, 0x1100, v2
	v_lshlrev_b32_e32 v0, 2, v0
	v_lshl_add_u64 v[212:213], v[230:231], 0, v[0:1]
	global_load_dword v91, v[212:213], off nt
.LBB0_516:
	s_or_b64 exec, exec, s[6:7]
	v_or_b32_e32 v0, 0x1140, v2
	v_cmp_lt_u32_e32 vcc, v0, v244
	s_and_saveexec_b64 s[6:7], vcc
	s_cbranch_execz .LBB0_518
	v_or_b32_e32 v0, 0x1140, v2
	v_lshlrev_b32_e32 v0, 2, v0
	v_lshl_add_u64 v[212:213], v[230:231], 0, v[0:1]
	global_load_dword v89, v[212:213], off nt
.LBB0_518:
	s_or_b64 exec, exec, s[6:7]
	v_or_b32_e32 v0, 0x1180, v2
	v_cmp_lt_u32_e32 vcc, v0, v244
	v_mov_b32_e32 v93, 0
	v_mov_b32_e32 v95, 0
	s_and_saveexec_b64 s[6:7], vcc
	s_cbranch_execz .LBB0_520
	v_or_b32_e32 v0, 0x1180, v2
	v_lshlrev_b32_e32 v0, 2, v0
	v_lshl_add_u64 v[212:213], v[230:231], 0, v[0:1]
	global_load_dword v95, v[212:213], off nt
.LBB0_520:
	s_or_b64 exec, exec, s[6:7]
	v_or_b32_e32 v0, 0x11c0, v2
	v_cmp_lt_u32_e32 vcc, v0, v244
	s_and_saveexec_b64 s[6:7], vcc
	s_cbranch_execz .LBB0_522
	v_or_b32_e32 v0, 0x11c0, v2
	v_lshlrev_b32_e32 v0, 2, v0
	v_lshl_add_u64 v[212:213], v[230:231], 0, v[0:1]
	global_load_dword v93, v[212:213], off nt
.LBB0_522:
	s_or_b64 exec, exec, s[6:7]
	v_or_b32_e32 v0, 0x1200, v2
	v_cmp_lt_u32_e32 vcc, v0, v244
	v_mov_b32_e32 v97, 0
	v_mov_b32_e32 v99, 0
	s_and_saveexec_b64 s[6:7], vcc
	s_cbranch_execz .LBB0_524
	v_or_b32_e32 v0, 0x1200, v2
	v_lshlrev_b32_e32 v0, 2, v0
	v_lshl_add_u64 v[212:213], v[230:231], 0, v[0:1]
	s_waitcnt vmcnt(48)
	global_load_dword v99, v[212:213], off nt
.LBB0_524:
	s_or_b64 exec, exec, s[6:7]
	v_or_b32_e32 v0, 0x1240, v2
	v_cmp_lt_u32_e32 vcc, v0, v244
	s_and_saveexec_b64 s[6:7], vcc
	s_cbranch_execz .LBB0_526
	v_or_b32_e32 v0, 0x1240, v2
	v_lshlrev_b32_e32 v0, 2, v0
	v_lshl_add_u64 v[212:213], v[230:231], 0, v[0:1]
	global_load_dword v97, v[212:213], off nt
.LBB0_526:
	s_or_b64 exec, exec, s[6:7]
	v_or_b32_e32 v0, 0x1280, v2
	v_cmp_lt_u32_e32 vcc, v0, v244
	v_mov_b32_e32 v101, 0
	v_mov_b32_e32 v103, 0
	s_and_saveexec_b64 s[6:7], vcc
	s_cbranch_execz .LBB0_528
	v_or_b32_e32 v0, 0x1280, v2
	v_lshlrev_b32_e32 v0, 2, v0
	v_lshl_add_u64 v[212:213], v[230:231], 0, v[0:1]
	global_load_dword v103, v[212:213], off nt
.LBB0_528:
	s_or_b64 exec, exec, s[6:7]
	v_or_b32_e32 v0, 0x12c0, v2
	v_cmp_lt_u32_e32 vcc, v0, v244
	s_and_saveexec_b64 s[6:7], vcc
	s_cbranch_execz .LBB0_530
	v_or_b32_e32 v0, 0x12c0, v2
	v_lshlrev_b32_e32 v0, 2, v0
	v_lshl_add_u64 v[212:213], v[230:231], 0, v[0:1]
	global_load_dword v101, v[212:213], off nt
; template <int NJ>
; DI void select_row(const float* row, int n, u64* bmrow, int lane) {
;     ...
;   for (int jj = 0; jj < NJ; ++jj) {
;     const int idx = jj * 64 + lane;
;     unsigned k = 0;
;     if (idx < n) { unsigned u = __float_as_uint(__builtin_nontemporal_load(row + idx)); k = (u & 0x80000000u) ? ~u : (u | 0x80000000u); }
;     key[jj] = k;
;   }
.LBB0_530:
	s_or_b64 exec, exec, s[6:7]
	v_or_b32_e32 v0, 0x1300, v2
	v_cmp_lt_u32_e32 vcc, v0, v244
	v_mov_b32_e32 v105, 0
	v_mov_b32_e32 v107, 0
	s_and_saveexec_b64 s[6:7], vcc
	s_cbranch_execz .LBB0_532
	v_or_b32_e32 v0, 0x1300, v2
	v_lshlrev_b32_e32 v0, 2, v0
	v_lshl_add_u64 v[212:213], v[230:231], 0, v[0:1]
	global_load_dword v107, v[212:213], off nt
.LBB0_532:
	s_or_b64 exec, exec, s[6:7]
	v_or_b32_e32 v0, 0x1340, v2
	v_cmp_lt_u32_e32 vcc, v0, v244
	s_and_saveexec_b64 s[6:7], vcc
	s_cbranch_execz .LBB0_534
	v_or_b32_e32 v0, 0x1340, v2
	v_lshlrev_b32_e32 v0, 2, v0
	v_lshl_add_u64 v[212:213], v[230:231], 0, v[0:1]
	global_load_dword v105, v[212:213], off nt
.LBB0_534:
	s_or_b64 exec, exec, s[6:7]
	v_or_b32_e32 v0, 0x1380, v2
	v_cmp_lt_u32_e32 vcc, v0, v244
	v_mov_b32_e32 v109, 0
	v_mov_b32_e32 v111, 0
	s_and_saveexec_b64 s[6:7], vcc
	s_cbranch_execz .LBB0_536
	v_or_b32_e32 v0, 0x1380, v2
	v_lshlrev_b32_e32 v0, 2, v0
	v_lshl_add_u64 v[212:213], v[230:231], 0, v[0:1]
	global_load_dword v111, v[212:213], off nt
.LBB0_536:
	s_or_b64 exec, exec, s[6:7]
	v_or_b32_e32 v0, 0x13c0, v2
	v_cmp_lt_u32_e32 vcc, v0, v244
	s_and_saveexec_b64 s[6:7], vcc
	s_cbranch_execz .LBB0_538
	v_or_b32_e32 v0, 0x13c0, v2
	v_lshlrev_b32_e32 v0, 2, v0
	v_lshl_add_u64 v[212:213], v[230:231], 0, v[0:1]
	global_load_dword v109, v[212:213], off nt
.LBB0_538:
	s_or_b64 exec, exec, s[6:7]
	v_or_b32_e32 v0, 0x1400, v2
	v_cmp_lt_u32_e32 vcc, v0, v244
	v_mov_b32_e32 v113, 0
	v_mov_b32_e32 v115, 0
	s_and_saveexec_b64 s[6:7], vcc
	s_cbranch_execz .LBB0_540
	v_or_b32_e32 v0, 0x1400, v2
	v_lshlrev_b32_e32 v0, 2, v0
	v_lshl_add_u64 v[212:213], v[230:231], 0, v[0:1]
	s_waitcnt vmcnt(48)
	global_load_dword v115, v[212:213], off nt
.LBB0_540:
	s_or_b64 exec, exec, s[6:7]
	v_or_b32_e32 v0, 0x1440, v2
	v_cmp_lt_u32_e32 vcc, v0, v244
	s_and_saveexec_b64 s[6:7], vcc
	s_cbranch_execz .LBB0_542
	v_or_b32_e32 v0, 0x1440, v2
	v_lshlrev_b32_e32 v0, 2, v0
	v_lshl_add_u64 v[212:213], v[230:231], 0, v[0:1]
	global_load_dword v113, v[212:213], off nt
.LBB0_542:
	s_or_b64 exec, exec, s[6:7]
	v_or_b32_e32 v0, 0x1480, v2
	v_cmp_lt_u32_e32 vcc, v0, v244
	v_mov_b32_e32 v117, 0
	v_mov_b32_e32 v119, 0
	s_and_saveexec_b64 s[6:7], vcc
	s_cbranch_execz .LBB0_544
	v_or_b32_e32 v0, 0x1480, v2
	v_lshlrev_b32_e32 v0, 2, v0
	v_lshl_add_u64 v[212:213], v[230:231], 0, v[0:1]
	global_load_dword v119, v[212:213], off nt
.LBB0_544:
	s_or_b64 exec, exec, s[6:7]
	v_cmp_lt_u32_e32 vcc, v42, v244
	s_and_saveexec_b64 s[6:7], vcc
	s_cbranch_execz .LBB0_546
	v_lshlrev_b32_e32 v0, 2, v42
	v_lshl_add_u64 v[212:213], v[230:231], 0, v[0:1]
	global_load_dword v117, v[212:213], off nt
.LBB0_546:
	s_or_b64 exec, exec, s[6:7]
	v_cmp_lt_u32_e32 vcc, v44, v244
	v_mov_b32_e32 v121, 0
	v_mov_b32_e32 v123, 0
	s_and_saveexec_b64 s[6:7], vcc
	s_cbranch_execz .LBB0_548
	v_lshlrev_b32_e32 v0, 2, v44
	v_lshl_add_u64 v[212:213], v[230:231], 0, v[0:1]
	global_load_dword v123, v[212:213], off nt
.LBB0_548:
	s_or_b64 exec, exec, s[6:7]
	v_cmp_lt_u32_e32 vcc, v46, v244
	s_and_saveexec_b64 s[6:7], vcc
	s_cbranch_execz .LBB0_550
	v_lshlrev_b32_e32 v0, 2, v46
	v_lshl_add_u64 v[212:213], v[230:231], 0, v[0:1]
	global_load_dword v121, v[212:213], off nt
.LBB0_550:
	s_or_b64 exec, exec, s[6:7]
	v_cmp_lt_u32_e32 vcc, v48, v244
	v_mov_b32_e32 v125, 0
	v_mov_b32_e32 v127, 0
	s_and_saveexec_b64 s[6:7], vcc
	s_cbranch_execz .LBB0_552
	v_lshlrev_b32_e32 v0, 2, v48
	v_lshl_add_u64 v[212:213], v[230:231], 0, v[0:1]
	global_load_dword v127, v[212:213], off nt
.LBB0_552:
	s_or_b64 exec, exec, s[6:7]
	v_cmp_lt_u32_e32 vcc, v50, v244
	s_and_saveexec_b64 s[6:7], vcc
	s_cbranch_execz .LBB0_554
	v_lshlrev_b32_e32 v0, 2, v50
	v_lshl_add_u64 v[212:213], v[230:231], 0, v[0:1]
	global_load_dword v125, v[212:213], off nt
.LBB0_554:
	s_or_b64 exec, exec, s[6:7]
	v_cmp_lt_u32_e32 vcc, v52, v244
	v_mov_b32_e32 v129, 0
	v_mov_b32_e32 v131, 0
	s_and_saveexec_b64 s[6:7], vcc
	s_cbranch_execz .LBB0_556
	v_lshlrev_b32_e32 v0, 2, v52
	v_lshl_add_u64 v[212:213], v[230:231], 0, v[0:1]
	s_waitcnt vmcnt(48)
	global_load_dword v131, v[212:213], off nt
.LBB0_556:
	s_or_b64 exec, exec, s[6:7]
	v_cmp_lt_u32_e32 vcc, v54, v244
	s_and_saveexec_b64 s[6:7], vcc
	s_cbranch_execz .LBB0_558
	v_lshlrev_b32_e32 v0, 2, v54
	v_lshl_add_u64 v[212:213], v[230:231], 0, v[0:1]
	global_load_dword v129, v[212:213], off nt
.LBB0_558:
	s_or_b64 exec, exec, s[6:7]
	v_cmp_lt_u32_e32 vcc, v56, v244
	v_mov_b32_e32 v133, 0
	v_mov_b32_e32 v135, 0
	s_and_saveexec_b64 s[6:7], vcc
	s_cbranch_execz .LBB0_560
	v_lshlrev_b32_e32 v0, 2, v56
	v_lshl_add_u64 v[212:213], v[230:231], 0, v[0:1]
	global_load_dword v135, v[212:213], off nt
.LBB0_560:
	s_or_b64 exec, exec, s[6:7]
	v_cmp_lt_u32_e32 vcc, v58, v244
	s_and_saveexec_b64 s[6:7], vcc
	s_cbranch_execz .LBB0_562
	v_lshlrev_b32_e32 v0, 2, v58
	v_lshl_add_u64 v[212:213], v[230:231], 0, v[0:1]
	global_load_dword v133, v[212:213], off nt
.LBB0_562:
	s_or_b64 exec, exec, s[6:7]
	v_cmp_lt_u32_e32 vcc, v60, v244
	v_mov_b32_e32 v137, 0
	v_mov_b32_e32 v139, 0
	s_and_saveexec_b64 s[6:7], vcc
	s_cbranch_execz .LBB0_564
	v_lshlrev_b32_e32 v0, 2, v60
	v_lshl_add_u64 v[212:213], v[230:231], 0, v[0:1]
	global_load_dword v139, v[212:213], off nt
.LBB0_564:
	s_or_b64 exec, exec, s[6:7]
	v_cmp_lt_u32_e32 vcc, v62, v244
	s_and_saveexec_b64 s[6:7], vcc
	s_cbranch_execz .LBB0_566
	v_lshlrev_b32_e32 v0, 2, v62
	v_lshl_add_u64 v[212:213], v[230:231], 0, v[0:1]
	global_load_dword v137, v[212:213], off nt
.LBB0_566:
	s_or_b64 exec, exec, s[6:7]
	v_cmp_lt_u32_e32 vcc, v64, v244
	v_mov_b32_e32 v141, 0
	v_mov_b32_e32 v143, 0
	s_and_saveexec_b64 s[6:7], vcc
	s_cbranch_execz .LBB0_568
	v_lshlrev_b32_e32 v0, 2, v64
	v_lshl_add_u64 v[212:213], v[230:231], 0, v[0:1]
	global_load_dword v143, v[212:213], off nt
; template <int NJ>
; DI void select_row(const float* row, int n, u64* bmrow, int lane) {
;     ...
; #pragma unroll
;   for (int jj = 0; jj < NJ; ++jj) {
;     const int idx = jj * 64 + lane;
;     unsigned k = 0;
;     if (idx < n) { unsigned u = __float_as_uint(__builtin_nontemporal_load(row + idx)); k = (u & 0x80000000u) ? ~u : (u | 0x80000000u); }
;     key[jj] = k;
;   }
.LBB0_568:
	s_or_b64 exec, exec, s[6:7]
	v_cmp_lt_u32_e32 vcc, v66, v244
	s_and_saveexec_b64 s[6:7], vcc
	s_cbranch_execz .LBB0_570
	v_lshlrev_b32_e32 v0, 2, v66
	v_lshl_add_u64 v[212:213], v[230:231], 0, v[0:1]
	global_load_dword v141, v[212:213], off nt
.LBB0_570:
	s_or_b64 exec, exec, s[6:7]
	v_cmp_lt_u32_e32 vcc, v68, v244
	v_mov_b32_e32 v145, 0
	v_mov_b32_e32 v147, 0
	s_and_saveexec_b64 s[6:7], vcc
	s_cbranch_execz .LBB0_572
	v_lshlrev_b32_e32 v0, 2, v68
	v_lshl_add_u64 v[212:213], v[230:231], 0, v[0:1]
	s_waitcnt vmcnt(48)
	global_load_dword v147, v[212:213], off nt
.LBB0_572:
	s_or_b64 exec, exec, s[6:7]
	v_cmp_lt_u32_e32 vcc, v70, v244
	s_and_saveexec_b64 s[6:7], vcc
	s_cbranch_execz .LBB0_574
	v_lshlrev_b32_e32 v0, 2, v70
	v_lshl_add_u64 v[212:213], v[230:231], 0, v[0:1]
	global_load_dword v145, v[212:213], off nt
.LBB0_574:
	s_or_b64 exec, exec, s[6:7]
	v_cmp_lt_u32_e32 vcc, v72, v244
	v_mov_b32_e32 v149, 0
	v_mov_b32_e32 v151, 0
	s_and_saveexec_b64 s[6:7], vcc
	s_cbranch_execz .LBB0_576
	v_lshlrev_b32_e32 v0, 2, v72
	v_lshl_add_u64 v[212:213], v[230:231], 0, v[0:1]
	global_load_dword v151, v[212:213], off nt
.LBB0_576:
	s_or_b64 exec, exec, s[6:7]
	v_cmp_lt_u32_e32 vcc, v74, v244
	s_and_saveexec_b64 s[6:7], vcc
	s_cbranch_execz .LBB0_578
	v_lshlrev_b32_e32 v0, 2, v74
	v_lshl_add_u64 v[212:213], v[230:231], 0, v[0:1]
	global_load_dword v149, v[212:213], off nt
.LBB0_578:
	s_or_b64 exec, exec, s[6:7]
	v_cmp_lt_u32_e32 vcc, v76, v244
	v_mov_b32_e32 v153, 0
	v_mov_b32_e32 v155, 0
	s_and_saveexec_b64 s[6:7], vcc
	s_cbranch_execz .LBB0_580
	v_lshlrev_b32_e32 v0, 2, v76
	v_lshl_add_u64 v[212:213], v[230:231], 0, v[0:1]
	global_load_dword v155, v[212:213], off nt
.LBB0_580:
	s_or_b64 exec, exec, s[6:7]
	v_cmp_lt_u32_e32 vcc, v78, v244
	s_and_saveexec_b64 s[6:7], vcc
	s_cbranch_execz .LBB0_582
	v_lshlrev_b32_e32 v0, 2, v78
	v_lshl_add_u64 v[212:213], v[230:231], 0, v[0:1]
	global_load_dword v153, v[212:213], off nt
.LBB0_582:
	s_or_b64 exec, exec, s[6:7]
	v_cmp_lt_u32_e32 vcc, v80, v244
	v_mov_b32_e32 v157, 0
	v_mov_b32_e32 v159, 0
	s_and_saveexec_b64 s[6:7], vcc
	s_cbranch_execz .LBB0_584
	v_lshlrev_b32_e32 v0, 2, v80
	v_lshl_add_u64 v[212:213], v[230:231], 0, v[0:1]
	global_load_dword v159, v[212:213], off nt
.LBB0_584:
	s_or_b64 exec, exec, s[6:7]
	v_cmp_lt_u32_e32 vcc, v82, v244
	s_and_saveexec_b64 s[6:7], vcc
	s_cbranch_execz .LBB0_586
	v_lshlrev_b32_e32 v0, 2, v82
	v_lshl_add_u64 v[212:213], v[230:231], 0, v[0:1]
	global_load_dword v157, v[212:213], off nt
.LBB0_586:
	s_or_b64 exec, exec, s[6:7]
	v_cmp_lt_u32_e32 vcc, v84, v244
	v_mov_b32_e32 v161, 0
	v_mov_b32_e32 v163, 0
	s_and_saveexec_b64 s[6:7], vcc
	s_cbranch_execz .LBB0_588
	v_lshlrev_b32_e32 v0, 2, v84
	v_lshl_add_u64 v[212:213], v[230:231], 0, v[0:1]
	s_waitcnt vmcnt(48)
	global_load_dword v163, v[212:213], off nt
.LBB0_588:
	s_or_b64 exec, exec, s[6:7]
	v_cmp_lt_u32_e32 vcc, v86, v244
	s_and_saveexec_b64 s[6:7], vcc
	s_cbranch_execz .LBB0_590
	v_lshlrev_b32_e32 v0, 2, v86
	v_lshl_add_u64 v[212:213], v[230:231], 0, v[0:1]
	global_load_dword v161, v[212:213], off nt
.LBB0_590:
	s_or_b64 exec, exec, s[6:7]
	v_cmp_lt_u32_e32 vcc, v88, v244
	v_mov_b32_e32 v165, 0
	v_mov_b32_e32 v167, 0
	s_and_saveexec_b64 s[6:7], vcc
	s_cbranch_execz .LBB0_592
	v_lshlrev_b32_e32 v0, 2, v88
	v_lshl_add_u64 v[212:213], v[230:231], 0, v[0:1]
	global_load_dword v167, v[212:213], off nt
.LBB0_592:
	s_or_b64 exec, exec, s[6:7]
	v_cmp_lt_u32_e32 vcc, v90, v244
	s_and_saveexec_b64 s[6:7], vcc
	s_cbranch_execz .LBB0_594
	v_lshlrev_b32_e32 v0, 2, v90
	v_lshl_add_u64 v[212:213], v[230:231], 0, v[0:1]
	global_load_dword v165, v[212:213], off nt
.LBB0_594:
	s_or_b64 exec, exec, s[6:7]
	v_cmp_lt_u32_e32 vcc, v92, v244
	v_mov_b32_e32 v169, 0
	v_mov_b32_e32 v171, 0
	s_and_saveexec_b64 s[6:7], vcc
	s_cbranch_execz .LBB0_596
	v_lshlrev_b32_e32 v0, 2, v92
	v_lshl_add_u64 v[212:213], v[230:231], 0, v[0:1]
	global_load_dword v171, v[212:213], off nt
.LBB0_596:
	s_or_b64 exec, exec, s[6:7]
	v_cmp_lt_u32_e32 vcc, v94, v244
	s_and_saveexec_b64 s[6:7], vcc
	s_cbranch_execz .LBB0_598
	v_lshlrev_b32_e32 v0, 2, v94
	v_lshl_add_u64 v[212:213], v[230:231], 0, v[0:1]
	global_load_dword v169, v[212:213], off nt
.LBB0_598:
	s_or_b64 exec, exec, s[6:7]
	v_cmp_lt_u32_e32 vcc, v96, v244
	v_mov_b32_e32 v173, 0
	v_mov_b32_e32 v175, 0
	s_and_saveexec_b64 s[6:7], vcc
	s_cbranch_execz .LBB0_600
	v_lshlrev_b32_e32 v0, 2, v96
	v_lshl_add_u64 v[212:213], v[230:231], 0, v[0:1]
	global_load_dword v175, v[212:213], off nt
.LBB0_600:
	s_or_b64 exec, exec, s[6:7]
	v_cmp_lt_u32_e32 vcc, v98, v244
	s_and_saveexec_b64 s[6:7], vcc
	s_cbranch_execz .LBB0_602
	v_lshlrev_b32_e32 v0, 2, v98
	v_lshl_add_u64 v[212:213], v[230:231], 0, v[0:1]
	global_load_dword v173, v[212:213], off nt
.LBB0_602:
	s_or_b64 exec, exec, s[6:7]
	v_cmp_lt_u32_e32 vcc, v100, v244
	v_mov_b32_e32 v177, 0
	v_mov_b32_e32 v179, 0
	s_and_saveexec_b64 s[6:7], vcc
	s_cbranch_execz .LBB0_604
	v_lshlrev_b32_e32 v0, 2, v100
	v_lshl_add_u64 v[212:213], v[230:231], 0, v[0:1]
	s_waitcnt vmcnt(48)
	global_load_dword v179, v[212:213], off nt
.LBB0_604:
	s_or_b64 exec, exec, s[6:7]
	v_cmp_lt_u32_e32 vcc, v102, v244
	s_and_saveexec_b64 s[6:7], vcc
	s_cbranch_execz .LBB0_606
	v_lshlrev_b32_e32 v0, 2, v102
	v_lshl_add_u64 v[212:213], v[230:231], 0, v[0:1]
	global_load_dword v177, v[212:213], off nt
.LBB0_606:
	s_or_b64 exec, exec, s[6:7]
	v_cmp_lt_u32_e32 vcc, v104, v244
	v_mov_b32_e32 v181, 0
	v_mov_b32_e32 v183, 0
	s_and_saveexec_b64 s[6:7], vcc
	s_cbranch_execz .LBB0_608
	v_lshlrev_b32_e32 v0, 2, v104
	v_lshl_add_u64 v[212:213], v[230:231], 0, v[0:1]
	global_load_dword v183, v[212:213], off nt
; template <int NJ>
; DI void select_row(const float* row, int n, u64* bmrow, int lane) {
;     ...
; #pragma unroll
;   for (int jj = 0; jj < NJ; ++jj) {
;     const int idx = jj * 64 + lane;
;     unsigned k = 0;
;     if (idx < n) { unsigned u = __float_as_uint(__builtin_nontemporal_load(row + idx)); k = (u & 0x80000000u) ? ~u : (u | 0x80000000u); }
;     key[jj] = k;
;   }
.LBB0_608:
	s_or_b64 exec, exec, s[6:7]
	v_cmp_lt_u32_e32 vcc, v106, v244
	s_and_saveexec_b64 s[6:7], vcc
	s_cbranch_execz .LBB0_610
	v_lshlrev_b32_e32 v0, 2, v106
	v_lshl_add_u64 v[212:213], v[230:231], 0, v[0:1]
	global_load_dword v181, v[212:213], off nt
.LBB0_610:
	s_or_b64 exec, exec, s[6:7]
	v_cmp_lt_u32_e32 vcc, v108, v244
	v_mov_b32_e32 v185, 0
	v_mov_b32_e32 v187, 0
	s_and_saveexec_b64 s[6:7], vcc
	s_cbranch_execz .LBB0_612
	v_lshlrev_b32_e32 v0, 2, v108
	v_lshl_add_u64 v[212:213], v[230:231], 0, v[0:1]
	global_load_dword v187, v[212:213], off nt
.LBB0_612:
	s_or_b64 exec, exec, s[6:7]
	v_cmp_lt_u32_e32 vcc, v110, v244
	s_and_saveexec_b64 s[6:7], vcc
	s_cbranch_execz .LBB0_614
	v_lshlrev_b32_e32 v0, 2, v110
	v_lshl_add_u64 v[212:213], v[230:231], 0, v[0:1]
	global_load_dword v185, v[212:213], off nt
.LBB0_614:
	s_or_b64 exec, exec, s[6:7]
	v_cmp_lt_u32_e32 vcc, v112, v244
	v_mov_b32_e32 v189, 0
	v_mov_b32_e32 v191, 0
	s_and_saveexec_b64 s[6:7], vcc
	s_cbranch_execz .LBB0_616
	v_lshlrev_b32_e32 v0, 2, v112
	v_lshl_add_u64 v[212:213], v[230:231], 0, v[0:1]
	global_load_dword v191, v[212:213], off nt
.LBB0_616:
	s_or_b64 exec, exec, s[6:7]
	v_cmp_lt_u32_e32 vcc, v114, v244
	s_and_saveexec_b64 s[6:7], vcc
	s_cbranch_execz .LBB0_618
	v_lshlrev_b32_e32 v0, 2, v114
	v_lshl_add_u64 v[212:213], v[230:231], 0, v[0:1]
	global_load_dword v189, v[212:213], off nt
.LBB0_618:
	s_or_b64 exec, exec, s[6:7]
	v_cmp_lt_u32_e32 vcc, v116, v244
	v_mov_b32_e32 v193, 0
	v_mov_b32_e32 v195, 0
	s_and_saveexec_b64 s[6:7], vcc
	s_cbranch_execz .LBB0_620
	v_lshlrev_b32_e32 v0, 2, v116
	v_lshl_add_u64 v[212:213], v[230:231], 0, v[0:1]
	s_waitcnt vmcnt(48)
	global_load_dword v195, v[212:213], off nt
.LBB0_620:
	s_or_b64 exec, exec, s[6:7]
	v_cmp_lt_u32_e32 vcc, v118, v244
	s_and_saveexec_b64 s[6:7], vcc
	s_cbranch_execz .LBB0_622
	v_lshlrev_b32_e32 v0, 2, v118
	v_lshl_add_u64 v[212:213], v[230:231], 0, v[0:1]
	global_load_dword v193, v[212:213], off nt
.LBB0_622:
	s_or_b64 exec, exec, s[6:7]
	v_cmp_lt_u32_e32 vcc, v120, v244
	v_mov_b32_e32 v197, 0
	v_mov_b32_e32 v199, 0
	s_and_saveexec_b64 s[6:7], vcc
	s_cbranch_execz .LBB0_624
	v_lshlrev_b32_e32 v0, 2, v120
	v_lshl_add_u64 v[212:213], v[230:231], 0, v[0:1]
	global_load_dword v199, v[212:213], off nt
.LBB0_624:
	s_or_b64 exec, exec, s[6:7]
	v_cmp_lt_u32_e32 vcc, v122, v244
	s_and_saveexec_b64 s[6:7], vcc
	s_cbranch_execz .LBB0_626
	v_lshlrev_b32_e32 v0, 2, v122
	v_lshl_add_u64 v[212:213], v[230:231], 0, v[0:1]
	global_load_dword v197, v[212:213], off nt
.LBB0_626:
	s_or_b64 exec, exec, s[6:7]
	v_cmp_lt_u32_e32 vcc, v124, v244
	v_mov_b32_e32 v234, 0
	v_mov_b32_e32 v235, 0
	s_and_saveexec_b64 s[6:7], vcc
	s_cbranch_execz .LBB0_628
	v_lshlrev_b32_e32 v0, 2, v124
	v_lshl_add_u64 v[212:213], v[230:231], 0, v[0:1]
	global_load_dword v235, v[212:213], off nt
.LBB0_628:
	s_or_b64 exec, exec, s[6:7]
	v_cmp_lt_u32_e32 vcc, v126, v244
	s_and_saveexec_b64 s[6:7], vcc
	s_cbranch_execz .LBB0_630
	v_lshlrev_b32_e32 v0, 2, v126
	v_lshl_add_u64 v[212:213], v[230:231], 0, v[0:1]
	global_load_dword v234, v[212:213], off nt
.LBB0_630:
	s_or_b64 exec, exec, s[6:7]
	v_cmp_lt_u32_e32 vcc, v128, v244
	v_mov_b32_e32 v242, 0
	v_mov_b32_e32 v243, 0
	s_and_saveexec_b64 s[6:7], vcc
	s_cbranch_execz .LBB0_632
	v_lshlrev_b32_e32 v0, 2, v128
	v_lshl_add_u64 v[212:213], v[230:231], 0, v[0:1]
	global_load_dword v243, v[212:213], off nt
.LBB0_632:
	s_or_b64 exec, exec, s[6:7]
	v_cmp_lt_u32_e32 vcc, v130, v244
	s_and_saveexec_b64 s[6:7], vcc
	s_cbranch_execz .LBB0_634
	v_lshlrev_b32_e32 v0, 2, v130
	v_lshl_add_u64 v[212:213], v[230:231], 0, v[0:1]
	global_load_dword v242, v[212:213], off nt
.LBB0_634:
	s_or_b64 exec, exec, s[6:7]
	s_waitcnt vmcnt(0)
	v_cmp_lt_u32_e64 s[6:7], v214, v244
	v_not_b32_e32 v0, v83
	v_cmp_gt_i32_e32 vcc, 0, v83
	s_nop 1
	v_cndmask_b32_e64 v0, -|v83|, v0, vcc
	v_cndmask_b32_e64 v83, 0, v0, s[6:7]
	v_cmp_lt_u32_e64 s[6:7], v216, v244
	v_not_b32_e32 v0, v81
	v_cmp_gt_i32_e32 vcc, 0, v81
	s_nop 1
	v_cndmask_b32_e64 v0, -|v81|, v0, vcc
	v_cndmask_b32_e64 v81, 0, v0, s[6:7]
	v_cmp_lt_u32_e64 s[6:7], v224, v244
	v_not_b32_e32 v0, v87
	v_cmp_gt_i32_e32 vcc, 0, v87
	s_nop 1
	v_cndmask_b32_e64 v0, -|v87|, v0, vcc
	v_cndmask_b32_e64 v87, 0, v0, s[6:7]
	v_or_b32_e32 v0, 0x10c0, v2
	v_cmp_lt_u32_e64 s[6:7], v0, v244
	v_not_b32_e32 v0, v85
	v_cmp_gt_i32_e32 vcc, 0, v85
	s_nop 1
	v_cndmask_b32_e64 v0, -|v85|, v0, vcc
	v_cndmask_b32_e64 v85, 0, v0, s[6:7]
	v_or_b32_e32 v0, 0x1100, v2
	v_cmp_lt_u32_e64 s[6:7], v0, v244
	v_not_b32_e32 v0, v91
	v_cmp_gt_i32_e32 vcc, 0, v91
	s_nop 1
	v_cndmask_b32_e64 v0, -|v91|, v0, vcc
	v_cndmask_b32_e64 v91, 0, v0, s[6:7]
	v_or_b32_e32 v0, 0x1140, v2
	v_cmp_lt_u32_e64 s[6:7], v0, v244
	v_not_b32_e32 v0, v89
	v_cmp_gt_i32_e32 vcc, 0, v89
	s_nop 1
	v_cndmask_b32_e64 v0, -|v89|, v0, vcc
	v_cndmask_b32_e64 v89, 0, v0, s[6:7]
	v_or_b32_e32 v0, 0x1180, v2
	v_cmp_lt_u32_e64 s[6:7], v0, v244
	v_not_b32_e32 v0, v95
	v_cmp_gt_i32_e32 vcc, 0, v95
	s_nop 1
	v_cndmask_b32_e64 v0, -|v95|, v0, vcc
	v_cndmask_b32_e64 v95, 0, v0, s[6:7]
	v_or_b32_e32 v0, 0x11c0, v2
	v_cmp_lt_u32_e64 s[6:7], v0, v244
	v_not_b32_e32 v0, v93
	v_cmp_gt_i32_e32 vcc, 0, v93
	s_nop 1
	v_cndmask_b32_e64 v0, -|v93|, v0, vcc
	v_cndmask_b32_e64 v93, 0, v0, s[6:7]
	v_or_b32_e32 v0, 0x1200, v2
	v_cmp_lt_u32_e64 s[6:7], v0, v244
	v_not_b32_e32 v0, v99
	v_cmp_gt_i32_e32 vcc, 0, v99
	s_nop 1
	v_cndmask_b32_e64 v0, -|v99|, v0, vcc
	v_cndmask_b32_e64 v99, 0, v0, s[6:7]
	v_or_b32_e32 v0, 0x1240, v2
	v_cmp_lt_u32_e64 s[6:7], v0, v244
	v_not_b32_e32 v0, v97
	v_cmp_gt_i32_e32 vcc, 0, v97
	s_nop 1
	v_cndmask_b32_e64 v0, -|v97|, v0, vcc
; template <int NJ>
; DI void select_row(const float* row, int n, u64* bmrow, int lane) {
;     ...
; #pragma unroll
;   for (int jj = 0; jj < NJ; ++jj) {
;     const int idx = jj * 64 + lane;
;     unsigned k = 0;
;     if (idx < n) { unsigned u = __float_as_uint(__builtin_nontemporal_load(row + idx)); k = (u & 0x80000000u) ? ~u : (u | 0x80000000u); }
;     key[jj] = k;
;   }
	v_cndmask_b32_e64 v97, 0, v0, s[6:7]
	v_or_b32_e32 v0, 0x1280, v2
	v_cmp_lt_u32_e64 s[6:7], v0, v244
	v_not_b32_e32 v0, v103
	v_cmp_gt_i32_e32 vcc, 0, v103
	s_nop 1
	v_cndmask_b32_e64 v0, -|v103|, v0, vcc
	v_cndmask_b32_e64 v103, 0, v0, s[6:7]
	v_or_b32_e32 v0, 0x12c0, v2
	v_cmp_lt_u32_e64 s[6:7], v0, v244
	v_not_b32_e32 v0, v101
	v_cmp_gt_i32_e32 vcc, 0, v101
	s_nop 1
	v_cndmask_b32_e64 v0, -|v101|, v0, vcc
	v_cndmask_b32_e64 v101, 0, v0, s[6:7]
	v_or_b32_e32 v0, 0x1300, v2
	v_cmp_lt_u32_e64 s[6:7], v0, v244
	v_not_b32_e32 v0, v107
	v_cmp_gt_i32_e32 vcc, 0, v107
	s_nop 1
	v_cndmask_b32_e64 v0, -|v107|, v0, vcc
	v_cndmask_b32_e64 v107, 0, v0, s[6:7]
	v_or_b32_e32 v0, 0x1340, v2
	v_cmp_lt_u32_e64 s[6:7], v0, v244
	v_not_b32_e32 v0, v105
	v_cmp_gt_i32_e32 vcc, 0, v105
	s_nop 1
	v_cndmask_b32_e64 v0, -|v105|, v0, vcc
	v_cndmask_b32_e64 v105, 0, v0, s[6:7]
	v_or_b32_e32 v0, 0x1380, v2
	v_cmp_lt_u32_e64 s[6:7], v0, v244
	v_not_b32_e32 v0, v111
	v_cmp_gt_i32_e32 vcc, 0, v111
	s_nop 1
	v_cndmask_b32_e64 v0, -|v111|, v0, vcc
	v_cndmask_b32_e64 v111, 0, v0, s[6:7]
	v_or_b32_e32 v0, 0x13c0, v2
	v_cmp_lt_u32_e64 s[6:7], v0, v244
	v_not_b32_e32 v0, v109
	v_cmp_gt_i32_e32 vcc, 0, v109
	s_nop 1
	v_cndmask_b32_e64 v0, -|v109|, v0, vcc
	v_cndmask_b32_e64 v109, 0, v0, s[6:7]
	v_or_b32_e32 v0, 0x1400, v2
	v_cmp_lt_u32_e64 s[6:7], v0, v244
	v_not_b32_e32 v0, v115
	v_cmp_gt_i32_e32 vcc, 0, v115
	s_nop 1
	v_cndmask_b32_e64 v0, -|v115|, v0, vcc
	v_cndmask_b32_e64 v115, 0, v0, s[6:7]
	v_or_b32_e32 v0, 0x1440, v2
	v_cmp_lt_u32_e64 s[6:7], v0, v244
	v_not_b32_e32 v0, v113
	v_cmp_gt_i32_e32 vcc, 0, v113
	s_nop 1
	v_cndmask_b32_e64 v0, -|v113|, v0, vcc
	v_cndmask_b32_e64 v113, 0, v0, s[6:7]
	v_or_b32_e32 v0, 0x1480, v2
	v_cmp_lt_u32_e64 s[6:7], v0, v244
	v_not_b32_e32 v0, v119
	v_cmp_gt_i32_e32 vcc, 0, v119
	s_nop 1
	v_cndmask_b32_e64 v0, -|v119|, v0, vcc
	v_cndmask_b32_e64 v119, 0, v0, s[6:7]
	v_cmp_lt_u32_e64 s[6:7], v42, v244
	v_not_b32_e32 v0, v117
	v_cmp_gt_i32_e32 vcc, 0, v117
	s_nop 1
	v_cndmask_b32_e64 v0, -|v117|, v0, vcc
	v_cndmask_b32_e64 v117, 0, v0, s[6:7]
	v_cmp_lt_u32_e64 s[6:7], v44, v244
	v_not_b32_e32 v0, v123
	v_cmp_gt_i32_e32 vcc, 0, v123
	s_nop 1
	v_cndmask_b32_e64 v0, -|v123|, v0, vcc
	v_cndmask_b32_e64 v123, 0, v0, s[6:7]
	v_cmp_lt_u32_e64 s[6:7], v46, v244
	v_not_b32_e32 v0, v121
	v_cmp_gt_i32_e32 vcc, 0, v121
	s_nop 1
	v_cndmask_b32_e64 v0, -|v121|, v0, vcc
	v_cndmask_b32_e64 v121, 0, v0, s[6:7]
	v_cmp_lt_u32_e64 s[6:7], v48, v244
	v_not_b32_e32 v0, v127
	v_cmp_gt_i32_e32 vcc, 0, v127
	s_nop 1
	v_cndmask_b32_e64 v0, -|v127|, v0, vcc
	v_cndmask_b32_e64 v127, 0, v0, s[6:7]
	v_cmp_lt_u32_e64 s[6:7], v50, v244
	v_not_b32_e32 v0, v125
	v_cmp_gt_i32_e32 vcc, 0, v125
	s_nop 1
	v_cndmask_b32_e64 v0, -|v125|, v0, vcc
	v_cndmask_b32_e64 v125, 0, v0, s[6:7]
	v_cmp_lt_u32_e64 s[6:7], v52, v244
	v_not_b32_e32 v0, v131
	v_cmp_gt_i32_e32 vcc, 0, v131
	s_nop 1
	v_cndmask_b32_e64 v0, -|v131|, v0, vcc
	v_cndmask_b32_e64 v131, 0, v0, s[6:7]
	v_cmp_lt_u32_e64 s[6:7], v54, v244
	v_not_b32_e32 v0, v129
	v_cmp_gt_i32_e32 vcc, 0, v129
	s_nop 1
	v_cndmask_b32_e64 v0, -|v129|, v0, vcc
	v_cndmask_b32_e64 v129, 0, v0, s[6:7]
	v_cmp_lt_u32_e64 s[6:7], v56, v244
	v_not_b32_e32 v0, v135
	v_cmp_gt_i32_e32 vcc, 0, v135
	s_nop 1
	v_cndmask_b32_e64 v0, -|v135|, v0, vcc
	v_cndmask_b32_e64 v135, 0, v0, s[6:7]
	v_cmp_lt_u32_e64 s[6:7], v58, v244
	v_not_b32_e32 v0, v133
	v_cmp_gt_i32_e32 vcc, 0, v133
	s_nop 1
	v_cndmask_b32_e64 v0, -|v133|, v0, vcc
	v_cndmask_b32_e64 v133, 0, v0, s[6:7]
	v_cmp_lt_u32_e64 s[6:7], v60, v244
	v_not_b32_e32 v0, v139
	v_cmp_gt_i32_e32 vcc, 0, v139
	s_nop 1
	v_cndmask_b32_e64 v0, -|v139|, v0, vcc
	v_cndmask_b32_e64 v139, 0, v0, s[6:7]
	v_cmp_lt_u32_e64 s[6:7], v62, v244
	v_not_b32_e32 v0, v137
	v_cmp_gt_i32_e32 vcc, 0, v137
	s_nop 1
	v_cndmask_b32_e64 v0, -|v137|, v0, vcc
	v_cndmask_b32_e64 v137, 0, v0, s[6:7]
	v_cmp_lt_u32_e64 s[6:7], v64, v244
	v_not_b32_e32 v0, v143
	v_cmp_gt_i32_e32 vcc, 0, v143
	s_nop 1
	v_cndmask_b32_e64 v0, -|v143|, v0, vcc
	v_cndmask_b32_e64 v143, 0, v0, s[6:7]
	v_cmp_lt_u32_e64 s[6:7], v66, v244
	v_not_b32_e32 v0, v141
	v_cmp_gt_i32_e32 vcc, 0, v141
	s_nop 1
	v_cndmask_b32_e64 v0, -|v141|, v0, vcc
	v_cndmask_b32_e64 v141, 0, v0, s[6:7]
	v_cmp_lt_u32_e64 s[6:7], v68, v244
	v_not_b32_e32 v0, v147
	v_cmp_gt_i32_e32 vcc, 0, v147
	s_nop 1
	v_cndmask_b32_e64 v0, -|v147|, v0, vcc
	v_cndmask_b32_e64 v147, 0, v0, s[6:7]
	v_cmp_lt_u32_e64 s[6:7], v70, v244
	v_not_b32_e32 v0, v145
	v_cmp_gt_i32_e32 vcc, 0, v145
	s_nop 1
	v_cndmask_b32_e64 v0, -|v145|, v0, vcc
	v_cndmask_b32_e64 v145, 0, v0, s[6:7]
	v_cmp_lt_u32_e64 s[6:7], v72, v244
	v_not_b32_e32 v0, v151
	v_cmp_gt_i32_e32 vcc, 0, v151
	s_nop 1
	v_cndmask_b32_e64 v0, -|v151|, v0, vcc
	v_cndmask_b32_e64 v151, 0, v0, s[6:7]
	v_cmp_lt_u32_e64 s[6:7], v74, v244
	v_not_b32_e32 v0, v149
	v_cmp_gt_i32_e32 vcc, 0, v149
	s_nop 1
	v_cndmask_b32_e64 v0, -|v149|, v0, vcc
	v_cndmask_b32_e64 v149, 0, v0, s[6:7]
	v_cmp_lt_u32_e64 s[6:7], v76, v244
	v_not_b32_e32 v0, v155
	v_cmp_gt_i32_e32 vcc, 0, v155
	s_nop 1
	v_cndmask_b32_e64 v0, -|v155|, v0, vcc
	v_cndmask_b32_e64 v155, 0, v0, s[6:7]
	v_cmp_lt_u32_e64 s[6:7], v78, v244
	v_not_b32_e32 v0, v153
	v_cmp_gt_i32_e32 vcc, 0, v153
	s_nop 1
	v_cndmask_b32_e64 v0, -|v153|, v0, vcc
	v_cndmask_b32_e64 v153, 0, v0, s[6:7]
	v_cmp_lt_u32_e64 s[6:7], v80, v244
	v_not_b32_e32 v0, v159
	v_cmp_gt_i32_e32 vcc, 0, v159
	s_nop 1
	v_cndmask_b32_e64 v0, -|v159|, v0, vcc
	v_cndmask_b32_e64 v159, 0, v0, s[6:7]
	v_cmp_lt_u32_e64 s[6:7], v82, v244
	v_not_b32_e32 v0, v157
	v_cmp_gt_i32_e32 vcc, 0, v157
	s_nop 1
	v_cndmask_b32_e64 v0, -|v157|, v0, vcc
; template <int NJ>
; DI void select_row(const float* row, int n, u64* bmrow, int lane) {
;     ...
; #pragma unroll
;   for (int jj = 0; jj < NJ; ++jj) {
;     const int idx = jj * 64 + lane;
;     unsigned k = 0;
;     if (idx < n) { unsigned u = __float_as_uint(__builtin_nontemporal_load(row + idx)); k = (u & 0x80000000u) ? ~u : (u | 0x80000000u); }
;     key[jj] = k;
;   }
	v_cndmask_b32_e64 v157, 0, v0, s[6:7]
	v_cmp_lt_u32_e64 s[6:7], v84, v244
	v_not_b32_e32 v0, v163
	v_cmp_gt_i32_e32 vcc, 0, v163
	s_nop 1
	v_cndmask_b32_e64 v0, -|v163|, v0, vcc
	v_cndmask_b32_e64 v163, 0, v0, s[6:7]
	v_cmp_lt_u32_e64 s[6:7], v86, v244
	v_not_b32_e32 v0, v161
	v_cmp_gt_i32_e32 vcc, 0, v161
	s_nop 1
	v_cndmask_b32_e64 v0, -|v161|, v0, vcc
	v_cndmask_b32_e64 v161, 0, v0, s[6:7]
	v_cmp_lt_u32_e64 s[6:7], v88, v244
	v_not_b32_e32 v0, v167
	v_cmp_gt_i32_e32 vcc, 0, v167
	s_nop 1
	v_cndmask_b32_e64 v0, -|v167|, v0, vcc
	v_cndmask_b32_e64 v167, 0, v0, s[6:7]
	v_cmp_lt_u32_e64 s[6:7], v90, v244
	v_not_b32_e32 v0, v165
	v_cmp_gt_i32_e32 vcc, 0, v165
	s_nop 1
	v_cndmask_b32_e64 v0, -|v165|, v0, vcc
	v_cndmask_b32_e64 v165, 0, v0, s[6:7]
	v_cmp_lt_u32_e64 s[6:7], v92, v244
	v_not_b32_e32 v0, v171
	v_cmp_gt_i32_e32 vcc, 0, v171
	s_nop 1
	v_cndmask_b32_e64 v0, -|v171|, v0, vcc
	v_cndmask_b32_e64 v171, 0, v0, s[6:7]
	v_cmp_lt_u32_e64 s[6:7], v94, v244
	v_not_b32_e32 v0, v169
	v_cmp_gt_i32_e32 vcc, 0, v169
	s_nop 1
	v_cndmask_b32_e64 v0, -|v169|, v0, vcc
	v_cndmask_b32_e64 v169, 0, v0, s[6:7]
	v_cmp_lt_u32_e64 s[6:7], v96, v244
	v_not_b32_e32 v0, v175
	v_cmp_gt_i32_e32 vcc, 0, v175
	s_nop 1
	v_cndmask_b32_e64 v0, -|v175|, v0, vcc
	v_cndmask_b32_e64 v175, 0, v0, s[6:7]
	v_cmp_lt_u32_e64 s[6:7], v98, v244
	v_not_b32_e32 v0, v173
	v_cmp_gt_i32_e32 vcc, 0, v173
	s_nop 1
	v_cndmask_b32_e64 v0, -|v173|, v0, vcc
	v_cndmask_b32_e64 v173, 0, v0, s[6:7]
	v_cmp_lt_u32_e64 s[6:7], v100, v244
	v_not_b32_e32 v0, v179
	v_cmp_gt_i32_e32 vcc, 0, v179
	s_nop 1
	v_cndmask_b32_e64 v0, -|v179|, v0, vcc
	v_cndmask_b32_e64 v179, 0, v0, s[6:7]
	v_cmp_lt_u32_e64 s[6:7], v102, v244
	v_not_b32_e32 v0, v177
	v_cmp_gt_i32_e32 vcc, 0, v177
	s_nop 1
	v_cndmask_b32_e64 v0, -|v177|, v0, vcc
	v_cndmask_b32_e64 v177, 0, v0, s[6:7]
	v_cmp_lt_u32_e64 s[6:7], v104, v244
	v_not_b32_e32 v0, v183
	v_cmp_gt_i32_e32 vcc, 0, v183
	s_nop 1
	v_cndmask_b32_e64 v0, -|v183|, v0, vcc
	v_cndmask_b32_e64 v183, 0, v0, s[6:7]
	v_cmp_lt_u32_e64 s[6:7], v106, v244
	v_not_b32_e32 v0, v181
	v_cmp_gt_i32_e32 vcc, 0, v181
	s_nop 1
	v_cndmask_b32_e64 v0, -|v181|, v0, vcc
	v_cndmask_b32_e64 v181, 0, v0, s[6:7]
	v_cmp_lt_u32_e64 s[6:7], v108, v244
	v_not_b32_e32 v0, v187
	v_cmp_gt_i32_e32 vcc, 0, v187
	s_nop 1
	v_cndmask_b32_e64 v0, -|v187|, v0, vcc
	v_cndmask_b32_e64 v187, 0, v0, s[6:7]
	v_cmp_lt_u32_e64 s[6:7], v110, v244
	v_not_b32_e32 v0, v185
	v_cmp_gt_i32_e32 vcc, 0, v185
	s_nop 1
	v_cndmask_b32_e64 v0, -|v185|, v0, vcc
	v_cndmask_b32_e64 v185, 0, v0, s[6:7]
	v_cmp_lt_u32_e64 s[6:7], v112, v244
	v_not_b32_e32 v0, v191
	v_cmp_gt_i32_e32 vcc, 0, v191
	s_nop 1
	v_cndmask_b32_e64 v0, -|v191|, v0, vcc
	v_cndmask_b32_e64 v191, 0, v0, s[6:7]
	v_cmp_lt_u32_e64 s[6:7], v114, v244
	v_not_b32_e32 v0, v189
	v_cmp_gt_i32_e32 vcc, 0, v189
	s_nop 1
	v_cndmask_b32_e64 v0, -|v189|, v0, vcc
	v_cndmask_b32_e64 v189, 0, v0, s[6:7]
	v_cmp_lt_u32_e64 s[6:7], v116, v244
	v_not_b32_e32 v0, v195
	v_cmp_gt_i32_e32 vcc, 0, v195
	s_nop 1
	v_cndmask_b32_e64 v0, -|v195|, v0, vcc
	v_cndmask_b32_e64 v195, 0, v0, s[6:7]
	v_cmp_lt_u32_e64 s[6:7], v118, v244
	v_not_b32_e32 v0, v193
	v_cmp_gt_i32_e32 vcc, 0, v193
	s_nop 1
	v_cndmask_b32_e64 v0, -|v193|, v0, vcc
	v_cndmask_b32_e64 v193, 0, v0, s[6:7]
	v_cmp_lt_u32_e64 s[6:7], v120, v244
	v_not_b32_e32 v0, v199
	v_cmp_gt_i32_e32 vcc, 0, v199
	s_nop 1
	v_cndmask_b32_e64 v0, -|v199|, v0, vcc
	v_cndmask_b32_e64 v199, 0, v0, s[6:7]
	v_cmp_lt_u32_e64 s[6:7], v122, v244
	v_not_b32_e32 v0, v197
	v_cmp_gt_i32_e32 vcc, 0, v197
	s_nop 1
	v_cndmask_b32_e64 v0, -|v197|, v0, vcc
	v_cndmask_b32_e64 v197, 0, v0, s[6:7]
	v_cmp_lt_u32_e64 s[6:7], v124, v244
	v_not_b32_e32 v0, v235
	v_cmp_gt_i32_e32 vcc, 0, v235
	s_nop 1
	v_cndmask_b32_e64 v0, -|v235|, v0, vcc
	v_cndmask_b32_e64 v235, 0, v0, s[6:7]
	v_cmp_lt_u32_e64 s[6:7], v126, v244
	v_not_b32_e32 v0, v234
	v_cmp_gt_i32_e32 vcc, 0, v234
	s_nop 1
	v_cndmask_b32_e64 v0, -|v234|, v0, vcc
	v_cndmask_b32_e64 v234, 0, v0, s[6:7]
	v_cmp_lt_u32_e64 s[6:7], v128, v244
	v_not_b32_e32 v0, v243
	v_cmp_gt_i32_e32 vcc, 0, v243
	s_nop 1
	v_cndmask_b32_e64 v0, -|v243|, v0, vcc
	v_cndmask_b32_e64 v243, 0, v0, s[6:7]
	v_cmp_lt_u32_e64 s[6:7], v130, v244
	v_not_b32_e32 v0, v242
	v_cmp_gt_i32_e32 vcc, 0, v242
	s_nop 1
	v_cndmask_b32_e64 v0, -|v242|, v0, vcc
	v_cndmask_b32_e64 v242, 0, v0, s[6:7]
	s_waitcnt vmcnt(31)
	v_not_b32_e32 v0, v30
	v_cmp_gt_i32_e32 vcc, 0, v30
	s_mov_b64 s[38:39], 0
	s_mov_b64 s[22:23], 0
	v_cndmask_b32_e64 v30, -|v30|, v0, vcc
	s_waitcnt vmcnt(30)
	v_not_b32_e32 v0, v28
	v_cmp_gt_i32_e32 vcc, 0, v28
	v_mov_b32_e32 v230, 0
	s_nop 0
	v_cndmask_b32_e64 v28, -|v28|, v0, vcc
	s_waitcnt vmcnt(29)
	v_not_b32_e32 v0, v26
	v_cmp_gt_i32_e32 vcc, 0, v26
	s_nop 1
	v_cndmask_b32_e64 v26, -|v26|, v0, vcc
	s_waitcnt vmcnt(28)
	v_not_b32_e32 v0, v24
	v_cmp_gt_i32_e32 vcc, 0, v24
	s_nop 1
	v_cndmask_b32_e64 v24, -|v24|, v0, vcc
	s_waitcnt vmcnt(27)
	v_not_b32_e32 v0, v22
	v_cmp_gt_i32_e32 vcc, 0, v22
	s_nop 1
	v_cndmask_b32_e64 v22, -|v22|, v0, vcc
	s_waitcnt vmcnt(26)
	v_not_b32_e32 v0, v20
	v_cmp_gt_i32_e32 vcc, 0, v20
	s_nop 1
	v_cndmask_b32_e64 v20, -|v20|, v0, vcc
	s_waitcnt vmcnt(25)
	v_not_b32_e32 v0, v18
	v_cmp_gt_i32_e32 vcc, 0, v18
	s_nop 1
	v_cndmask_b32_e64 v18, -|v18|, v0, vcc
	s_waitcnt vmcnt(24)
	v_not_b32_e32 v0, v16
	v_cmp_gt_i32_e32 vcc, 0, v16
	s_nop 1
	v_cndmask_b32_e64 v16, -|v16|, v0, vcc
	s_waitcnt vmcnt(23)
	v_not_b32_e32 v0, v14
	v_cmp_gt_i32_e32 vcc, 0, v14
	s_nop 1
	v_cndmask_b32_e64 v14, -|v14|, v0, vcc
	s_waitcnt vmcnt(22)
; DI int shflxi(int v, int m, int lane) { return __builtin_amdgcn_ds_bpermute((lane ^ m) << 2, v); }
; template <int NJ>
; DI void select_row(const float* row, int n, u64* bmrow, int lane) {
;     ...
; #pragma unroll
;   for (int jj = 0; jj < NJ; ++jj) {
;     const int idx = jj * 64 + lane;
;     unsigned k = 0;
;     if (idx < n) { unsigned u = __float_as_uint(__builtin_nontemporal_load(row + idx)); k = (u & 0x80000000u) ? ~u : (u | 0x80000000u); }
;     key[jj] = k;
;   }
;   unsigned km = 0;
; #pragma unroll
;   for (int jj = 0; jj < NJ; ++jj) km = (key[jj] > km) ? key[jj] : km;
; #pragma unroll
;   for (int o = 32; o > 0; o >>= 1) { const unsigned t = (unsigned)shflxi((int)km, o, lane); km = (t > km) ? t : km; }
;   unsigned lo = 0, hi = (km == 0xffffffffu) ? km : (km + 1u), T = 0;
;   bool exact = false;
;   {
;     unsigned cand = km & 0xff800000u;
	v_not_b32_e32 v0, v12
	v_cmp_gt_i32_e32 vcc, 0, v12
	s_nop 1
	v_cndmask_b32_e64 v12, -|v12|, v0, vcc
	s_waitcnt vmcnt(21)
	v_not_b32_e32 v0, v10
	v_cmp_gt_i32_e32 vcc, 0, v10
	s_nop 1
	v_cndmask_b32_e64 v10, -|v10|, v0, vcc
	s_waitcnt vmcnt(20)
	v_not_b32_e32 v0, v8
	v_cmp_gt_i32_e32 vcc, 0, v8
	s_nop 1
	v_cndmask_b32_e64 v8, -|v8|, v0, vcc
	s_waitcnt vmcnt(19)
	v_not_b32_e32 v0, v6
	v_cmp_gt_i32_e32 vcc, 0, v6
	s_nop 1
	v_cndmask_b32_e64 v6, -|v6|, v0, vcc
	s_waitcnt vmcnt(18)
	v_not_b32_e32 v0, v4
	v_cmp_gt_i32_e32 vcc, 0, v4
	s_nop 1
	v_cndmask_b32_e64 v4, -|v4|, v0, vcc
	s_waitcnt vmcnt(17)
	v_not_b32_e32 v0, v236
	v_cmp_gt_i32_e32 vcc, 0, v236
	s_nop 1
	v_cndmask_b32_e64 v240, -|v236|, v0, vcc
	s_waitcnt vmcnt(16)
	v_not_b32_e32 v0, v211
	v_cmp_gt_i32_e32 vcc, 0, v211
	s_nop 1
	v_cndmask_b32_e64 v236, -|v211|, v0, vcc
	s_waitcnt vmcnt(15)
	v_not_b32_e32 v0, v36
	v_cmp_gt_i32_e32 vcc, 0, v36
	s_nop 1
	v_cndmask_b32_e64 v211, -|v36|, v0, vcc
	s_waitcnt vmcnt(14)
	v_not_b32_e32 v0, v239
	v_cmp_gt_i32_e32 vcc, 0, v239
	v_mov_b32_e32 v36, 3
	s_nop 0
	v_cndmask_b32_e64 v239, -|v239|, v0, vcc
	s_waitcnt vmcnt(13)
	v_not_b32_e32 v0, v227
	v_cmp_gt_i32_e32 vcc, 0, v227
	s_nop 1
	v_cndmask_b32_e64 v227, -|v227|, v0, vcc
	s_waitcnt vmcnt(12)
	v_not_b32_e32 v0, v253
	v_cmp_gt_i32_e32 vcc, 0, v253
	s_nop 1
	v_cndmask_b32_e64 v253, -|v253|, v0, vcc
	s_waitcnt vmcnt(11)
	v_not_b32_e32 v0, v252
	v_cmp_gt_i32_e32 vcc, 0, v252
	s_nop 1
	v_cndmask_b32_e64 v252, -|v252|, v0, vcc
	s_waitcnt vmcnt(10)
	v_not_b32_e32 v0, v251
	v_cmp_gt_i32_e32 vcc, 0, v251
	s_nop 1
	v_cndmask_b32_e64 v251, -|v251|, v0, vcc
	s_waitcnt vmcnt(9)
	v_not_b32_e32 v0, v250
	v_cmp_gt_i32_e32 vcc, 0, v250
	s_nop 1
	v_cndmask_b32_e64 v250, -|v250|, v0, vcc
	s_waitcnt vmcnt(8)
	v_not_b32_e32 v0, v249
	v_cmp_gt_i32_e32 vcc, 0, v249
	s_nop 1
	v_cndmask_b32_e64 v249, -|v249|, v0, vcc
	s_waitcnt vmcnt(7)
	v_not_b32_e32 v0, v248
	v_cmp_gt_i32_e32 vcc, 0, v248
	s_nop 1
	v_cndmask_b32_e64 v248, -|v248|, v0, vcc
	s_waitcnt vmcnt(6)
	v_not_b32_e32 v0, v247
	v_cmp_gt_i32_e32 vcc, 0, v247
	s_nop 1
	v_cndmask_b32_e64 v247, -|v247|, v0, vcc
	s_waitcnt vmcnt(5)
	v_not_b32_e32 v0, v246
	v_cmp_gt_i32_e32 vcc, 0, v246
	s_nop 1
	v_cndmask_b32_e64 v246, -|v246|, v0, vcc
	s_waitcnt vmcnt(4)
	v_not_b32_e32 v0, v245
	v_cmp_gt_i32_e32 vcc, 0, v245
	s_nop 1
	v_cndmask_b32_e64 v245, -|v245|, v0, vcc
	s_waitcnt vmcnt(3)
	v_not_b32_e32 v0, v233
	v_cmp_gt_i32_e32 vcc, 0, v233
	s_nop 1
	v_cndmask_b32_e64 v244, -|v233|, v0, vcc
	s_waitcnt vmcnt(2)
	v_not_b32_e32 v0, v232
	v_cmp_gt_i32_e32 vcc, 0, v232
	s_nop 1
	v_cndmask_b32_e64 v233, -|v232|, v0, vcc
	s_waitcnt vmcnt(1)
	v_not_b32_e32 v0, v34
	v_cmp_gt_i32_e32 vcc, 0, v34
	s_nop 1
	v_cndmask_b32_e64 v232, -|v34|, v0, vcc
	s_waitcnt vmcnt(0)
	v_not_b32_e32 v0, v32
	v_cmp_gt_i32_e32 vcc, 0, v32
	s_nop 1
	v_cndmask_b32_e64 v0, -|v32|, v0, vcc
	v_max_u32_e32 v32, v77, v79
	v_max3_u32 v32, v73, v75, v32
	v_max3_u32 v32, v69, v71, v32
	v_max3_u32 v32, v65, v67, v32
	v_max3_u32 v32, v61, v63, v32
	v_max3_u32 v32, v57, v59, v32
	v_max3_u32 v32, v51, v55, v32
	v_max3_u32 v32, v49, v53, v32
	v_max3_u32 v32, v45, v47, v32
	v_max3_u32 v32, v41, v43, v32
	v_max3_u32 v32, v37, v39, v32
	v_max3_u32 v32, v33, v35, v32
	v_max3_u32 v32, v29, v31, v32
	v_max3_u32 v32, v25, v27, v32
	v_max3_u32 v32, v21, v23, v32
	v_max3_u32 v32, v17, v19, v32
	v_max3_u32 v32, v28, v30, v32
	v_max3_u32 v32, v24, v26, v32
	v_max3_u32 v32, v20, v22, v32
	v_max3_u32 v32, v16, v18, v32
	v_max3_u32 v32, v12, v14, v32
	v_max3_u32 v32, v8, v10, v32
	v_max3_u32 v32, v4, v6, v32
	v_max3_u32 v32, v236, v240, v32
	v_max3_u32 v32, v239, v211, v32
	v_max3_u32 v32, v253, v227, v32
	v_max3_u32 v32, v251, v252, v32
	v_max3_u32 v32, v249, v250, v32
	v_max3_u32 v32, v247, v248, v32
	v_max3_u32 v32, v245, v246, v32
	v_max3_u32 v32, v233, v244, v32
	v_max3_u32 v32, v0, v232, v32
	v_max3_u32 v32, v81, v83, v32
	v_max3_u32 v32, v85, v87, v32
	v_max3_u32 v32, v89, v91, v32
	v_max3_u32 v32, v93, v95, v32
	v_max3_u32 v32, v97, v99, v32
	v_max3_u32 v32, v101, v103, v32
	v_max3_u32 v32, v105, v107, v32
	v_max3_u32 v32, v109, v111, v32
	v_max3_u32 v32, v113, v115, v32
	v_max3_u32 v32, v117, v119, v32
	v_max3_u32 v32, v121, v123, v32
	v_max3_u32 v32, v125, v127, v32
	v_max3_u32 v32, v129, v131, v32
	v_max3_u32 v32, v133, v135, v32
	v_max3_u32 v32, v137, v139, v32
	v_max3_u32 v32, v141, v143, v32
	v_max3_u32 v32, v145, v147, v32
	v_max3_u32 v32, v149, v151, v32
	v_max3_u32 v32, v153, v155, v32
	v_max3_u32 v32, v157, v159, v32
	v_max3_u32 v32, v161, v163, v32
	v_max3_u32 v32, v165, v167, v32
	v_max3_u32 v32, v169, v171, v32
	v_max3_u32 v32, v173, v175, v32
	v_max3_u32 v32, v177, v179, v32
	v_max3_u32 v32, v181, v183, v32
	v_max3_u32 v32, v185, v187, v32
	v_max3_u32 v32, v189, v191, v32
	v_max3_u32 v32, v193, v195, v32
	v_max3_u32 v32, v197, v199, v32
	v_max3_u32 v32, v234, v235, v32
	v_max3_u32 v32, v242, v243, v32
	ds_bpermute_b32 v34, v5, v32
	s_waitcnt lgkmcnt(0)
	v_max_u32_e32 v32, v34, v32
	ds_bpermute_b32 v34, v7, v32
	s_waitcnt lgkmcnt(0)
	v_max_u32_e32 v32, v34, v32
	ds_bpermute_b32 v34, v9, v32
	s_waitcnt lgkmcnt(0)
	v_max_u32_e32 v32, v34, v32
	ds_bpermute_b32 v34, v11, v32
	s_waitcnt lgkmcnt(0)
	v_max_u32_e32 v32, v34, v32
	ds_bpermute_b32 v34, v13, v32
	s_waitcnt lgkmcnt(0)
	v_max_u32_e32 v32, v34, v32
	ds_bpermute_b32 v34, v15, v32
	s_waitcnt lgkmcnt(0)
	v_max_u32_e32 v32, v34, v32
	v_add_u32_e64 v34, v32, 1 clamp
	v_and_b32_e32 v231, 0xff800000, v32
	v_mov_b32_e32 v32, 0
	s_branch .LBB0_638

; template <int NJ>
; DI void select_row(const float* row, int n, u64* bmrow, int lane) {
;     ...
; #pragma unroll
;   for (int jj = 0; jj < NJ; ++jj) {
;     const int idx = jj * 64 + lane;
;     unsigned k = 0;
;     if (idx < n) { unsigned u = __float_as_uint(__builtin_nontemporal_load(row + idx)); k = (u & 0x80000000u) ? ~u : (u | 0x80000000u); }
;     key[jj] = k;
;   }
.LBB0_652:
	s_andn2_saveexec_b64 s[18:19], s[18:19]
	s_cbranch_execz .LBB0_725
	v_cmp_lt_u32_e32 vcc, v132, v244
	v_mov_b32_e32 v4, 0
	v_mov_b32_e32 v6, 0
	s_and_saveexec_b64 s[6:7], vcc
	s_cbranch_execz .LBB0_655
	v_lshlrev_b32_e32 v0, 2, v132
	v_lshl_add_u64 v[212:213], v[230:231], 0, v[0:1]
	global_load_dword v6, v[212:213], off nt
.LBB0_655:
	s_or_b64 exec, exec, s[6:7]
	v_cmp_lt_u32_e32 vcc, v134, v244
	s_and_saveexec_b64 s[6:7], vcc
	s_cbranch_execz .LBB0_657
	v_lshlrev_b32_e32 v0, 2, v134
	v_lshl_add_u64 v[212:213], v[230:231], 0, v[0:1]
	global_load_dword v4, v[212:213], off nt
.LBB0_657:
	s_or_b64 exec, exec, s[6:7]
	v_cmp_lt_u32_e32 vcc, v136, v244
	v_mov_b32_e32 v8, 0
	v_mov_b32_e32 v10, 0
	s_and_saveexec_b64 s[6:7], vcc
	s_cbranch_execz .LBB0_659
	v_lshlrev_b32_e32 v0, 2, v136
	v_lshl_add_u64 v[212:213], v[230:231], 0, v[0:1]
	global_load_dword v10, v[212:213], off nt
.LBB0_659:
	s_or_b64 exec, exec, s[6:7]
	v_cmp_lt_u32_e32 vcc, v138, v244
	s_and_saveexec_b64 s[6:7], vcc
	s_cbranch_execz .LBB0_661
	v_lshlrev_b32_e32 v0, 2, v138
	v_lshl_add_u64 v[212:213], v[230:231], 0, v[0:1]
	global_load_dword v8, v[212:213], off nt
.LBB0_661:
	s_or_b64 exec, exec, s[6:7]
	v_cmp_lt_u32_e32 vcc, v140, v244
	v_mov_b32_e32 v12, 0
	v_mov_b32_e32 v14, 0
	s_and_saveexec_b64 s[6:7], vcc
	s_cbranch_execz .LBB0_663
	v_lshlrev_b32_e32 v0, 2, v140
	v_lshl_add_u64 v[212:213], v[230:231], 0, v[0:1]
	global_load_dword v14, v[212:213], off nt
.LBB0_663:
	s_or_b64 exec, exec, s[6:7]
	v_cmp_lt_u32_e32 vcc, v142, v244
	s_and_saveexec_b64 s[6:7], vcc
	s_cbranch_execz .LBB0_665
	v_lshlrev_b32_e32 v0, 2, v142
	v_lshl_add_u64 v[212:213], v[230:231], 0, v[0:1]
	global_load_dword v12, v[212:213], off nt
.LBB0_665:
	s_or_b64 exec, exec, s[6:7]
	v_cmp_lt_u32_e32 vcc, v144, v244
	v_mov_b32_e32 v16, 0
	v_mov_b32_e32 v18, 0
	s_and_saveexec_b64 s[6:7], vcc
	s_cbranch_execz .LBB0_667
	v_lshlrev_b32_e32 v0, 2, v144
	v_lshl_add_u64 v[212:213], v[230:231], 0, v[0:1]
	global_load_dword v18, v[212:213], off nt
.LBB0_667:
	s_or_b64 exec, exec, s[6:7]
	v_cmp_lt_u32_e32 vcc, v146, v244
	s_and_saveexec_b64 s[6:7], vcc
	s_cbranch_execz .LBB0_669
	v_lshlrev_b32_e32 v0, 2, v146
	v_lshl_add_u64 v[212:213], v[230:231], 0, v[0:1]
	global_load_dword v16, v[212:213], off nt
.LBB0_669:
	s_or_b64 exec, exec, s[6:7]
	v_cmp_lt_u32_e32 vcc, v148, v244
	v_mov_b32_e32 v20, 0
	v_mov_b32_e32 v22, 0
	s_and_saveexec_b64 s[6:7], vcc
	s_cbranch_execz .LBB0_671
	v_lshlrev_b32_e32 v0, 2, v148
	v_lshl_add_u64 v[212:213], v[230:231], 0, v[0:1]
	s_waitcnt vmcnt(48)
	global_load_dword v22, v[212:213], off nt
.LBB0_671:
	s_or_b64 exec, exec, s[6:7]
	v_cmp_lt_u32_e32 vcc, v150, v244
	s_and_saveexec_b64 s[6:7], vcc
	s_cbranch_execz .LBB0_673
	v_lshlrev_b32_e32 v0, 2, v150
	v_lshl_add_u64 v[212:213], v[230:231], 0, v[0:1]
	global_load_dword v20, v[212:213], off nt
.LBB0_673:
	s_or_b64 exec, exec, s[6:7]
	v_cmp_lt_u32_e32 vcc, v152, v244
	v_mov_b32_e32 v24, 0
	v_mov_b32_e32 v26, 0
	s_and_saveexec_b64 s[6:7], vcc
	s_cbranch_execz .LBB0_675
	v_lshlrev_b32_e32 v0, 2, v152
	v_lshl_add_u64 v[212:213], v[230:231], 0, v[0:1]
	global_load_dword v26, v[212:213], off nt
.LBB0_675:
	s_or_b64 exec, exec, s[6:7]
	v_cmp_lt_u32_e32 vcc, v154, v244
	s_and_saveexec_b64 s[6:7], vcc
	s_cbranch_execz .LBB0_677
	v_lshlrev_b32_e32 v0, 2, v154
	v_lshl_add_u64 v[212:213], v[230:231], 0, v[0:1]
	global_load_dword v24, v[212:213], off nt
.LBB0_677:
	s_or_b64 exec, exec, s[6:7]
	v_cmp_lt_u32_e32 vcc, v156, v244
	v_mov_b32_e32 v28, 0
	v_mov_b32_e32 v30, 0
	s_and_saveexec_b64 s[6:7], vcc
	s_cbranch_execz .LBB0_679
	v_lshlrev_b32_e32 v0, 2, v156
	v_lshl_add_u64 v[212:213], v[230:231], 0, v[0:1]
	global_load_dword v30, v[212:213], off nt
.LBB0_679:
	s_or_b64 exec, exec, s[6:7]
	v_cmp_lt_u32_e32 vcc, v158, v244
	s_and_saveexec_b64 s[6:7], vcc
	s_cbranch_execz .LBB0_681
	v_lshlrev_b32_e32 v0, 2, v158
	v_lshl_add_u64 v[212:213], v[230:231], 0, v[0:1]
	global_load_dword v28, v[212:213], off nt
.LBB0_681:
	s_or_b64 exec, exec, s[6:7]
	v_cmp_lt_u32_e32 vcc, v160, v244
	v_mov_b32_e32 v81, 0
	v_mov_b32_e32 v83, 0
	s_and_saveexec_b64 s[6:7], vcc
	s_cbranch_execz .LBB0_683
	v_lshlrev_b32_e32 v0, 2, v160
	v_lshl_add_u64 v[212:213], v[230:231], 0, v[0:1]
	global_load_dword v83, v[212:213], off nt
.LBB0_683:
	s_or_b64 exec, exec, s[6:7]
	v_cmp_lt_u32_e32 vcc, v162, v244
	s_and_saveexec_b64 s[6:7], vcc
	s_cbranch_execz .LBB0_685
	v_lshlrev_b32_e32 v0, 2, v162
	v_lshl_add_u64 v[212:213], v[230:231], 0, v[0:1]
	global_load_dword v81, v[212:213], off nt
.LBB0_685:
	s_or_b64 exec, exec, s[6:7]
	v_cmp_lt_u32_e32 vcc, v164, v244
	v_mov_b32_e32 v85, 0
	v_mov_b32_e32 v87, 0
	s_and_saveexec_b64 s[6:7], vcc
	s_cbranch_execz .LBB0_687
	v_lshlrev_b32_e32 v0, 2, v164
	v_lshl_add_u64 v[212:213], v[230:231], 0, v[0:1]
	s_waitcnt vmcnt(48)
	global_load_dword v87, v[212:213], off nt
.LBB0_687:
	s_or_b64 exec, exec, s[6:7]
	v_cmp_lt_u32_e32 vcc, v166, v244
	s_and_saveexec_b64 s[6:7], vcc
	s_cbranch_execz .LBB0_689
	v_lshlrev_b32_e32 v0, 2, v166
	v_lshl_add_u64 v[212:213], v[230:231], 0, v[0:1]
	global_load_dword v85, v[212:213], off nt
.LBB0_689:
	s_or_b64 exec, exec, s[6:7]
	v_cmp_lt_u32_e32 vcc, v168, v244
	v_mov_b32_e32 v89, 0
	v_mov_b32_e32 v91, 0
	s_and_saveexec_b64 s[6:7], vcc
	s_cbranch_execz .LBB0_691
	v_lshlrev_b32_e32 v0, 2, v168
	v_lshl_add_u64 v[212:213], v[230:231], 0, v[0:1]
	global_load_dword v91, v[212:213], off nt
.LBB0_691:
	s_or_b64 exec, exec, s[6:7]
	v_cmp_lt_u32_e32 vcc, v170, v244
	s_and_saveexec_b64 s[6:7], vcc
	s_cbranch_execz .LBB0_693
	v_lshlrev_b32_e32 v0, 2, v170
	v_lshl_add_u64 v[212:213], v[230:231], 0, v[0:1]
	global_load_dword v89, v[212:213], off nt
; template <int NJ>
; DI void select_row(const float* row, int n, u64* bmrow, int lane) {
;     ...
; #pragma unroll
;   for (int jj = 0; jj < NJ; ++jj) {
;     const int idx = jj * 64 + lane;
;     unsigned k = 0;
;     if (idx < n) { unsigned u = __float_as_uint(__builtin_nontemporal_load(row + idx)); k = (u & 0x80000000u) ? ~u : (u | 0x80000000u); }
;     key[jj] = k;
;   }
.LBB0_693:
	s_or_b64 exec, exec, s[6:7]
	v_cmp_lt_u32_e32 vcc, v172, v244
	v_mov_b32_e32 v93, 0
	v_mov_b32_e32 v95, 0
	s_and_saveexec_b64 s[6:7], vcc
	s_cbranch_execz .LBB0_695
	v_lshlrev_b32_e32 v0, 2, v172
	v_lshl_add_u64 v[212:213], v[230:231], 0, v[0:1]
	global_load_dword v95, v[212:213], off nt
.LBB0_695:
	s_or_b64 exec, exec, s[6:7]
	v_cmp_lt_u32_e32 vcc, v174, v244
	s_and_saveexec_b64 s[6:7], vcc
	s_cbranch_execz .LBB0_697
	v_lshlrev_b32_e32 v0, 2, v174
	v_lshl_add_u64 v[212:213], v[230:231], 0, v[0:1]
	global_load_dword v93, v[212:213], off nt
.LBB0_697:
	s_or_b64 exec, exec, s[6:7]
	v_cmp_lt_u32_e32 vcc, v176, v244
	v_mov_b32_e32 v97, 0
	v_mov_b32_e32 v99, 0
	s_and_saveexec_b64 s[6:7], vcc
	s_cbranch_execz .LBB0_699
	v_lshlrev_b32_e32 v0, 2, v176
	v_lshl_add_u64 v[212:213], v[230:231], 0, v[0:1]
	global_load_dword v99, v[212:213], off nt
.LBB0_699:
	s_or_b64 exec, exec, s[6:7]
	v_cmp_lt_u32_e32 vcc, v178, v244
	s_and_saveexec_b64 s[6:7], vcc
	s_cbranch_execz .LBB0_701
	v_lshlrev_b32_e32 v0, 2, v178
	v_lshl_add_u64 v[212:213], v[230:231], 0, v[0:1]
	global_load_dword v97, v[212:213], off nt
.LBB0_701:
	s_or_b64 exec, exec, s[6:7]
	v_cmp_lt_u32_e32 vcc, v180, v244
	v_mov_b32_e32 v101, 0
	v_mov_b32_e32 v32, 0
	s_and_saveexec_b64 s[6:7], vcc
	s_cbranch_execz .LBB0_703
	v_lshlrev_b32_e32 v0, 2, v180
	v_lshl_add_u64 v[212:213], v[230:231], 0, v[0:1]
	s_waitcnt vmcnt(48)
	global_load_dword v32, v[212:213], off nt
.LBB0_703:
	s_or_b64 exec, exec, s[6:7]
	v_cmp_lt_u32_e32 vcc, v182, v244
	s_and_saveexec_b64 s[6:7], vcc
	s_cbranch_execz .LBB0_705
	v_lshlrev_b32_e32 v0, 2, v182
	v_lshl_add_u64 v[212:213], v[230:231], 0, v[0:1]
	global_load_dword v101, v[212:213], off nt
.LBB0_705:
	s_or_b64 exec, exec, s[6:7]
	v_cmp_lt_u32_e32 vcc, v184, v244
	v_mov_b32_e32 v103, 0
	v_mov_b32_e32 v105, 0
	s_and_saveexec_b64 s[6:7], vcc
	s_cbranch_execz .LBB0_707
	v_lshlrev_b32_e32 v0, 2, v184
	v_lshl_add_u64 v[212:213], v[230:231], 0, v[0:1]
	global_load_dword v105, v[212:213], off nt
.LBB0_707:
	s_or_b64 exec, exec, s[6:7]
	v_cmp_lt_u32_e32 vcc, v186, v244
	s_and_saveexec_b64 s[6:7], vcc
	s_cbranch_execz .LBB0_709
	v_lshlrev_b32_e32 v0, 2, v186
	v_lshl_add_u64 v[212:213], v[230:231], 0, v[0:1]
	global_load_dword v103, v[212:213], off nt
.LBB0_709:
	s_or_b64 exec, exec, s[6:7]
	v_cmp_lt_u32_e32 vcc, v188, v244
	v_mov_b32_e32 v107, 0
	v_mov_b32_e32 v109, 0
	s_and_saveexec_b64 s[6:7], vcc
	s_cbranch_execz .LBB0_711
	v_lshlrev_b32_e32 v0, 2, v188
	v_lshl_add_u64 v[212:213], v[230:231], 0, v[0:1]
	global_load_dword v109, v[212:213], off nt
.LBB0_711:
	s_or_b64 exec, exec, s[6:7]
	v_cmp_lt_u32_e32 vcc, v190, v244
	s_and_saveexec_b64 s[6:7], vcc
	s_cbranch_execz .LBB0_713
	v_lshlrev_b32_e32 v0, 2, v190
	v_lshl_add_u64 v[212:213], v[230:231], 0, v[0:1]
	global_load_dword v107, v[212:213], off nt
.LBB0_713:
	s_or_b64 exec, exec, s[6:7]
	v_cmp_lt_u32_e32 vcc, v192, v244
	v_mov_b32_e32 v111, 0
	v_mov_b32_e32 v113, 0
	s_and_saveexec_b64 s[6:7], vcc
	s_cbranch_execz .LBB0_715
	v_lshlrev_b32_e32 v0, 2, v192
	v_lshl_add_u64 v[212:213], v[230:231], 0, v[0:1]
	global_load_dword v113, v[212:213], off nt
.LBB0_715:
	s_or_b64 exec, exec, s[6:7]
	v_cmp_lt_u32_e32 vcc, v194, v244
	s_and_saveexec_b64 s[6:7], vcc
	s_cbranch_execz .LBB0_717
	v_lshlrev_b32_e32 v0, 2, v194
	v_lshl_add_u64 v[212:213], v[230:231], 0, v[0:1]
	global_load_dword v111, v[212:213], off nt
.LBB0_717:
	s_or_b64 exec, exec, s[6:7]
	s_waitcnt vmcnt(0)
	v_cmp_lt_u32_e64 s[6:7], v132, v244
	v_not_b32_e32 v0, v6
	v_cmp_gt_i32_e32 vcc, 0, v6
	s_nop 1
	v_cndmask_b32_e64 v0, -|v6|, v0, vcc
	v_cndmask_b32_e64 v6, 0, v0, s[6:7]
	v_cmp_lt_u32_e64 s[6:7], v134, v244
	v_not_b32_e32 v0, v4
	v_cmp_gt_i32_e32 vcc, 0, v4
	s_nop 1
	v_cndmask_b32_e64 v0, -|v4|, v0, vcc
	v_cndmask_b32_e64 v4, 0, v0, s[6:7]
	v_cmp_lt_u32_e64 s[6:7], v136, v244
	v_not_b32_e32 v0, v10
	v_cmp_gt_i32_e32 vcc, 0, v10
	s_nop 1
	v_cndmask_b32_e64 v0, -|v10|, v0, vcc
	v_cndmask_b32_e64 v10, 0, v0, s[6:7]
	v_cmp_lt_u32_e64 s[6:7], v138, v244
	v_not_b32_e32 v0, v8
	v_cmp_gt_i32_e32 vcc, 0, v8
	s_nop 1
	v_cndmask_b32_e64 v0, -|v8|, v0, vcc
	v_cndmask_b32_e64 v8, 0, v0, s[6:7]
	v_cmp_lt_u32_e64 s[6:7], v140, v244
	v_not_b32_e32 v0, v14
	v_cmp_gt_i32_e32 vcc, 0, v14
	s_nop 1
	v_cndmask_b32_e64 v0, -|v14|, v0, vcc
	v_cndmask_b32_e64 v14, 0, v0, s[6:7]
	v_cmp_lt_u32_e64 s[6:7], v142, v244
	v_not_b32_e32 v0, v12
	v_cmp_gt_i32_e32 vcc, 0, v12
	s_nop 1
	v_cndmask_b32_e64 v0, -|v12|, v0, vcc
	v_cndmask_b32_e64 v12, 0, v0, s[6:7]
	v_cmp_lt_u32_e64 s[6:7], v144, v244
	v_not_b32_e32 v0, v18
	v_cmp_gt_i32_e32 vcc, 0, v18
	s_nop 1
	v_cndmask_b32_e64 v0, -|v18|, v0, vcc
	v_cndmask_b32_e64 v18, 0, v0, s[6:7]
	v_cmp_lt_u32_e64 s[6:7], v146, v244
	v_not_b32_e32 v0, v16
	v_cmp_gt_i32_e32 vcc, 0, v16
	s_nop 1
	v_cndmask_b32_e64 v0, -|v16|, v0, vcc
	v_cndmask_b32_e64 v16, 0, v0, s[6:7]
	v_cmp_lt_u32_e64 s[6:7], v148, v244
	v_not_b32_e32 v0, v22
	v_cmp_gt_i32_e32 vcc, 0, v22
	s_nop 1
	v_cndmask_b32_e64 v0, -|v22|, v0, vcc
	v_cndmask_b32_e64 v22, 0, v0, s[6:7]
	v_cmp_lt_u32_e64 s[6:7], v150, v244
	v_not_b32_e32 v0, v20
	v_cmp_gt_i32_e32 vcc, 0, v20
	s_nop 1
	v_cndmask_b32_e64 v0, -|v20|, v0, vcc
	v_cndmask_b32_e64 v20, 0, v0, s[6:7]
	v_cmp_lt_u32_e64 s[6:7], v152, v244
	v_not_b32_e32 v0, v26
	v_cmp_gt_i32_e32 vcc, 0, v26
	s_nop 1
	v_cndmask_b32_e64 v0, -|v26|, v0, vcc
; DI int shflxi(int v, int m, int lane) { return __builtin_amdgcn_ds_bpermute((lane ^ m) << 2, v); }
; template <int NJ>
; DI void select_row(const float* row, int n, u64* bmrow, int lane) {
;     ...
; #pragma unroll
;   for (int jj = 0; jj < NJ; ++jj) {
;     const int idx = jj * 64 + lane;
;     unsigned k = 0;
;     if (idx < n) { unsigned u = __float_as_uint(__builtin_nontemporal_load(row + idx)); k = (u & 0x80000000u) ? ~u : (u | 0x80000000u); }
;     key[jj] = k;
;   }
;   unsigned km = 0;
; #pragma unroll
;   for (int jj = 0; jj < NJ; ++jj) km = (key[jj] > km) ? key[jj] : km;
; #pragma unroll
;   for (int o = 32; o > 0; o >>= 1) { const unsigned t = (unsigned)shflxi((int)km, o, lane); km = (t > km) ? t : km; }
;   unsigned lo = 0, hi = (km == 0xffffffffu) ? km : (km + 1u), T = 0;
;   bool exact = false;
;   {
;     unsigned cand = km & 0xff800000u;
	v_cndmask_b32_e64 v26, 0, v0, s[6:7]
	v_cmp_lt_u32_e64 s[6:7], v154, v244
	v_not_b32_e32 v0, v24
	v_cmp_gt_i32_e32 vcc, 0, v24
	s_nop 1
	v_cndmask_b32_e64 v0, -|v24|, v0, vcc
	v_cndmask_b32_e64 v24, 0, v0, s[6:7]
	v_cmp_lt_u32_e64 s[6:7], v156, v244
	v_not_b32_e32 v0, v30
	v_cmp_gt_i32_e32 vcc, 0, v30
	s_nop 1
	v_cndmask_b32_e64 v0, -|v30|, v0, vcc
	v_cndmask_b32_e64 v30, 0, v0, s[6:7]
	v_cmp_lt_u32_e64 s[6:7], v158, v244
	v_not_b32_e32 v0, v28
	v_cmp_gt_i32_e32 vcc, 0, v28
	s_nop 1
	v_cndmask_b32_e64 v0, -|v28|, v0, vcc
	v_cndmask_b32_e64 v28, 0, v0, s[6:7]
	v_cmp_lt_u32_e64 s[6:7], v160, v244
	v_not_b32_e32 v0, v83
	v_cmp_gt_i32_e32 vcc, 0, v83
	s_nop 1
	v_cndmask_b32_e64 v0, -|v83|, v0, vcc
	v_cndmask_b32_e64 v83, 0, v0, s[6:7]
	v_cmp_lt_u32_e64 s[6:7], v162, v244
	v_not_b32_e32 v0, v81
	v_cmp_gt_i32_e32 vcc, 0, v81
	s_nop 1
	v_cndmask_b32_e64 v0, -|v81|, v0, vcc
	v_cndmask_b32_e64 v81, 0, v0, s[6:7]
	v_cmp_lt_u32_e64 s[6:7], v164, v244
	v_not_b32_e32 v0, v87
	v_cmp_gt_i32_e32 vcc, 0, v87
	s_nop 1
	v_cndmask_b32_e64 v0, -|v87|, v0, vcc
	v_cndmask_b32_e64 v87, 0, v0, s[6:7]
	v_cmp_lt_u32_e64 s[6:7], v166, v244
	v_not_b32_e32 v0, v85
	v_cmp_gt_i32_e32 vcc, 0, v85
	s_nop 1
	v_cndmask_b32_e64 v0, -|v85|, v0, vcc
	v_cndmask_b32_e64 v85, 0, v0, s[6:7]
	v_cmp_lt_u32_e64 s[6:7], v168, v244
	v_not_b32_e32 v0, v91
	v_cmp_gt_i32_e32 vcc, 0, v91
	s_nop 1
	v_cndmask_b32_e64 v0, -|v91|, v0, vcc
	v_cndmask_b32_e64 v91, 0, v0, s[6:7]
	v_cmp_lt_u32_e64 s[6:7], v170, v244
	v_not_b32_e32 v0, v89
	v_cmp_gt_i32_e32 vcc, 0, v89
	s_nop 1
	v_cndmask_b32_e64 v0, -|v89|, v0, vcc
	v_cndmask_b32_e64 v89, 0, v0, s[6:7]
	v_cmp_lt_u32_e64 s[6:7], v172, v244
	v_not_b32_e32 v0, v95
	v_cmp_gt_i32_e32 vcc, 0, v95
	s_nop 1
	v_cndmask_b32_e64 v0, -|v95|, v0, vcc
	v_cndmask_b32_e64 v95, 0, v0, s[6:7]
	v_cmp_lt_u32_e64 s[6:7], v174, v244
	v_not_b32_e32 v0, v93
	v_cmp_gt_i32_e32 vcc, 0, v93
	s_nop 1
	v_cndmask_b32_e64 v0, -|v93|, v0, vcc
	v_cndmask_b32_e64 v93, 0, v0, s[6:7]
	v_cmp_lt_u32_e64 s[6:7], v176, v244
	v_not_b32_e32 v0, v99
	v_cmp_gt_i32_e32 vcc, 0, v99
	s_nop 1
	v_cndmask_b32_e64 v0, -|v99|, v0, vcc
	v_cndmask_b32_e64 v99, 0, v0, s[6:7]
	v_cmp_lt_u32_e64 s[6:7], v178, v244
	v_not_b32_e32 v0, v97
	v_cmp_gt_i32_e32 vcc, 0, v97
	s_nop 1
	v_cndmask_b32_e64 v0, -|v97|, v0, vcc
	v_cndmask_b32_e64 v97, 0, v0, s[6:7]
	v_cmp_lt_u32_e64 s[6:7], v180, v244
	v_not_b32_e32 v0, v32
	v_cmp_gt_i32_e32 vcc, 0, v32
	s_nop 1
	v_cndmask_b32_e64 v0, -|v32|, v0, vcc
	v_cndmask_b32_e64 v32, 0, v0, s[6:7]
	v_cmp_lt_u32_e64 s[6:7], v182, v244
	v_not_b32_e32 v0, v101
	v_cmp_gt_i32_e32 vcc, 0, v101
	s_nop 1
	v_cndmask_b32_e64 v0, -|v101|, v0, vcc
	v_cndmask_b32_e64 v101, 0, v0, s[6:7]
	v_cmp_lt_u32_e64 s[6:7], v184, v244
	v_not_b32_e32 v0, v105
	v_cmp_gt_i32_e32 vcc, 0, v105
	s_nop 1
	v_cndmask_b32_e64 v0, -|v105|, v0, vcc
	v_cndmask_b32_e64 v105, 0, v0, s[6:7]
	v_cmp_lt_u32_e64 s[6:7], v186, v244
	v_not_b32_e32 v0, v103
	v_cmp_gt_i32_e32 vcc, 0, v103
	s_nop 1
	v_cndmask_b32_e64 v0, -|v103|, v0, vcc
	v_cndmask_b32_e64 v103, 0, v0, s[6:7]
	v_cmp_lt_u32_e64 s[6:7], v188, v244
	v_not_b32_e32 v0, v109
	v_cmp_gt_i32_e32 vcc, 0, v109
	s_nop 1
	v_cndmask_b32_e64 v0, -|v109|, v0, vcc
	v_cndmask_b32_e64 v109, 0, v0, s[6:7]
	v_cmp_lt_u32_e64 s[6:7], v190, v244
	v_not_b32_e32 v0, v107
	v_cmp_gt_i32_e32 vcc, 0, v107
	s_nop 1
	v_cndmask_b32_e64 v0, -|v107|, v0, vcc
	v_cndmask_b32_e64 v107, 0, v0, s[6:7]
	v_cmp_lt_u32_e64 s[6:7], v192, v244
	v_not_b32_e32 v0, v113
	v_cmp_gt_i32_e32 vcc, 0, v113
	s_nop 1
	v_cndmask_b32_e64 v0, -|v113|, v0, vcc
	v_cndmask_b32_e64 v113, 0, v0, s[6:7]
	v_cmp_lt_u32_e64 s[6:7], v194, v244
	v_not_b32_e32 v0, v111
	v_cmp_gt_i32_e32 vcc, 0, v111
	s_nop 1
	v_cndmask_b32_e64 v0, -|v111|, v0, vcc
	v_cndmask_b32_e64 v111, 0, v0, s[6:7]
	v_max_u32_e32 v0, v77, v79
	v_max3_u32 v0, v73, v75, v0
	v_max3_u32 v0, v69, v71, v0
	v_max3_u32 v0, v65, v67, v0
	v_max3_u32 v0, v61, v63, v0
	v_max3_u32 v0, v57, v59, v0
	v_max3_u32 v0, v51, v55, v0
	v_max3_u32 v0, v49, v53, v0
	v_max3_u32 v0, v45, v47, v0
	v_max3_u32 v0, v41, v43, v0
	v_max3_u32 v0, v37, v39, v0
	v_max3_u32 v0, v33, v35, v0
	v_max3_u32 v0, v29, v31, v0
	v_max3_u32 v0, v25, v27, v0
	v_max3_u32 v0, v21, v23, v0
	v_max3_u32 v0, v17, v19, v0
	v_max3_u32 v0, v4, v6, v0
	v_max3_u32 v0, v8, v10, v0
	v_max3_u32 v0, v12, v14, v0
	v_max3_u32 v0, v16, v18, v0
	v_max3_u32 v0, v20, v22, v0
	v_max3_u32 v0, v24, v26, v0
	v_max3_u32 v0, v28, v30, v0
	v_max3_u32 v0, v81, v83, v0
	v_max3_u32 v0, v85, v87, v0
	v_max3_u32 v0, v89, v91, v0
	v_max3_u32 v0, v93, v95, v0
	v_max3_u32 v0, v97, v99, v0
	v_max3_u32 v0, v101, v32, v0
	v_max3_u32 v0, v103, v105, v0
	v_max3_u32 v0, v107, v109, v0
	v_max3_u32 v0, v111, v113, v0
	ds_bpermute_b32 v34, v5, v0
	s_mov_b64 s[38:39], 0
	s_mov_b64 s[22:23], 0
	v_mov_b32_e32 v38, 3
	s_waitcnt lgkmcnt(0)
	v_max_u32_e32 v0, v34, v0
	ds_bpermute_b32 v34, v7, v0
	s_waitcnt lgkmcnt(0)
	v_max_u32_e32 v0, v34, v0
	ds_bpermute_b32 v34, v9, v0
	s_waitcnt lgkmcnt(0)
	v_max_u32_e32 v0, v34, v0
	ds_bpermute_b32 v34, v11, v0
	s_waitcnt lgkmcnt(0)
	v_max_u32_e32 v0, v34, v0
	ds_bpermute_b32 v34, v13, v0
	s_waitcnt lgkmcnt(0)
	v_max_u32_e32 v0, v34, v0
	ds_bpermute_b32 v36, v15, v0
	v_mov_b32_e32 v34, 0
	s_waitcnt lgkmcnt(0)
	v_max_u32_e32 v0, v36, v0
	v_add_u32_e64 v36, v0, 1 clamp
	v_and_b32_e32 v115, 0xff800000, v0
	v_mov_b32_e32 v0, 0
	s_branch .LBB0_721

; template <int NJ>
; DI void select_row(const float* row, int n, u64* bmrow, int lane) {
;     ...
; #pragma unroll
;   for (int jj = 0; jj < NJ; ++jj) {
;     const int idx = jj * 64 + lane;
;     unsigned k = 0;
;     if (idx < n) { unsigned u = __float_as_uint(__builtin_nontemporal_load(row + idx)); k = (u & 0x80000000u) ? ~u : (u | 0x80000000u); }
;     key[jj] = k;
;   }
.LBB0_727:
	v_lshl_add_u64 v[232:233], v[230:231], 0, v[0:1]
	global_load_dword v43, v[232:233], off nt
	global_load_dword v41, v[232:233], off offset:256 nt
	global_load_dword v39, v[232:233], off offset:512 nt
	global_load_dword v45, v[232:233], off offset:768 nt
	v_or_b32_e32 v0, 0x100, v2
	v_cmp_lt_u32_e32 vcc, v0, v244
	v_mov_b32_e32 v4, 0
	v_mov_b32_e32 v6, 0
	s_and_saveexec_b64 s[6:7], vcc
	s_cbranch_execz .LBB0_729
	global_load_dword v6, v[232:233], off offset:1024 nt
.LBB0_729:
	s_or_b64 exec, exec, s[6:7]
	v_or_b32_e32 v0, 0x140, v2
	v_cmp_lt_u32_e32 vcc, v0, v244
	s_and_saveexec_b64 s[6:7], vcc
	s_cbranch_execz .LBB0_731
	global_load_dword v4, v[232:233], off offset:1280 nt
.LBB0_731:
	s_or_b64 exec, exec, s[6:7]
	v_or_b32_e32 v0, 0x180, v2
	v_cmp_lt_u32_e32 vcc, v0, v244
	v_mov_b32_e32 v8, 0
	v_mov_b32_e32 v10, 0
	s_and_saveexec_b64 s[6:7], vcc
	s_cbranch_execz .LBB0_733
	global_load_dword v10, v[232:233], off offset:1536 nt
.LBB0_733:
	s_or_b64 exec, exec, s[6:7]
	v_or_b32_e32 v0, 0x1c0, v2
	v_cmp_lt_u32_e32 vcc, v0, v244
	s_and_saveexec_b64 s[6:7], vcc
	s_cbranch_execz .LBB0_735
	global_load_dword v8, v[232:233], off offset:1792 nt
.LBB0_735:
	s_or_b64 exec, exec, s[6:7]
	v_or_b32_e32 v0, 0x200, v2
	v_cmp_lt_u32_e32 vcc, v0, v244
	v_mov_b32_e32 v12, 0
	v_mov_b32_e32 v14, 0
	s_and_saveexec_b64 s[6:7], vcc
	s_cbranch_execz .LBB0_737
	global_load_dword v14, v[232:233], off offset:2048 nt
.LBB0_737:
	s_or_b64 exec, exec, s[6:7]
	v_or_b32_e32 v0, 0x240, v2
	v_cmp_lt_u32_e32 vcc, v0, v244
	s_and_saveexec_b64 s[6:7], vcc
	s_cbranch_execz .LBB0_739
	global_load_dword v12, v[232:233], off offset:2304 nt
.LBB0_739:
	s_or_b64 exec, exec, s[6:7]
	v_or_b32_e32 v0, 0x280, v2
	v_cmp_lt_u32_e32 vcc, v0, v244
	v_mov_b32_e32 v16, 0
	v_mov_b32_e32 v17, 0
	s_and_saveexec_b64 s[6:7], vcc
	s_cbranch_execz .LBB0_741
	global_load_dword v17, v[232:233], off offset:2560 nt
.LBB0_741:
	s_or_b64 exec, exec, s[6:7]
	v_or_b32_e32 v0, 0x2c0, v2
	v_cmp_lt_u32_e32 vcc, v0, v244
	s_and_saveexec_b64 s[6:7], vcc
	s_cbranch_execz .LBB0_743
	global_load_dword v16, v[232:233], off offset:2816 nt
.LBB0_743:
	s_or_b64 exec, exec, s[6:7]
	v_or_b32_e32 v0, 0x300, v2
	v_cmp_lt_u32_e32 vcc, v0, v244
	v_mov_b32_e32 v18, 0
	v_mov_b32_e32 v19, 0
	s_and_saveexec_b64 s[6:7], vcc
	s_cbranch_execz .LBB0_745
	s_waitcnt vmcnt(48)
	global_load_dword v19, v[232:233], off offset:3072 nt
.LBB0_745:
	s_or_b64 exec, exec, s[6:7]
	v_or_b32_e32 v0, 0x340, v2
	v_cmp_lt_u32_e32 vcc, v0, v244
	s_and_saveexec_b64 s[6:7], vcc
	s_cbranch_execz .LBB0_747
	global_load_dword v18, v[232:233], off offset:3328 nt
.LBB0_747:
	s_or_b64 exec, exec, s[6:7]
	v_or_b32_e32 v0, 0x380, v2
	v_cmp_lt_u32_e32 vcc, v0, v244
	v_mov_b32_e32 v20, 0
	v_mov_b32_e32 v21, 0
	s_and_saveexec_b64 s[6:7], vcc
	s_cbranch_execz .LBB0_749
	global_load_dword v21, v[232:233], off offset:3584 nt
.LBB0_749:
	s_or_b64 exec, exec, s[6:7]
	v_or_b32_e32 v0, 0x3c0, v2
	v_cmp_lt_u32_e32 vcc, v0, v244
	s_and_saveexec_b64 s[6:7], vcc
	s_cbranch_execz .LBB0_751
	global_load_dword v20, v[232:233], off offset:3840 nt
.LBB0_751:
	s_or_b64 exec, exec, s[6:7]
	v_cmp_lt_u32_e32 vcc, v196, v244
	v_mov_b32_e32 v22, 0
	v_mov_b32_e32 v23, 0
	s_and_saveexec_b64 s[6:7], vcc
	s_cbranch_execz .LBB0_753
	v_lshlrev_b32_e32 v0, 2, v196
	v_lshl_add_u64 v[24:25], v[230:231], 0, v[0:1]
	global_load_dword v23, v[24:25], off nt
.LBB0_753:
	s_or_b64 exec, exec, s[6:7]
	v_cmp_lt_u32_e32 vcc, v198, v244
	s_and_saveexec_b64 s[6:7], vcc
	s_cbranch_execz .LBB0_755
	v_lshlrev_b32_e32 v0, 2, v198
	v_lshl_add_u64 v[24:25], v[230:231], 0, v[0:1]
	global_load_dword v22, v[24:25], off nt
.LBB0_755:
	s_or_b64 exec, exec, s[6:7]
	v_cmp_lt_u32_e32 vcc, v200, v244
	v_mov_b32_e32 v24, 0
	v_mov_b32_e32 v25, 0
	s_and_saveexec_b64 s[6:7], vcc
	s_cbranch_execz .LBB0_757
	v_lshlrev_b32_e32 v0, 2, v200
	v_lshl_add_u64 v[26:27], v[230:231], 0, v[0:1]
	global_load_dword v25, v[26:27], off nt
.LBB0_757:
	s_or_b64 exec, exec, s[6:7]
	v_or_b32_e32 v0, 0x4c0, v2
	v_cmp_lt_u32_e32 vcc, v0, v244
	s_and_saveexec_b64 s[6:7], vcc
	s_cbranch_execz .LBB0_759
	v_or_b32_e32 v0, 0x4c0, v2
	v_lshlrev_b32_e32 v0, 2, v0
	v_lshl_add_u64 v[26:27], v[230:231], 0, v[0:1]
	global_load_dword v24, v[26:27], off nt
.LBB0_759:
	s_or_b64 exec, exec, s[6:7]
	v_or_b32_e32 v0, 0x500, v2
	v_cmp_lt_u32_e32 vcc, v0, v244
	v_mov_b32_e32 v26, 0
	v_mov_b32_e32 v27, 0
	s_and_saveexec_b64 s[6:7], vcc
	s_cbranch_execz .LBB0_761
	v_or_b32_e32 v0, 0x500, v2
	v_lshlrev_b32_e32 v0, 2, v0
	v_lshl_add_u64 v[28:29], v[230:231], 0, v[0:1]
	s_waitcnt vmcnt(48)
	global_load_dword v27, v[28:29], off nt
.LBB0_761:
	s_or_b64 exec, exec, s[6:7]
	v_or_b32_e32 v0, 0x540, v2
	v_cmp_lt_u32_e32 vcc, v0, v244
	s_and_saveexec_b64 s[6:7], vcc
	s_cbranch_execz .LBB0_763
	v_or_b32_e32 v0, 0x540, v2
	v_lshlrev_b32_e32 v0, 2, v0
	v_lshl_add_u64 v[28:29], v[230:231], 0, v[0:1]
	global_load_dword v26, v[28:29], off nt
.LBB0_763:
	s_or_b64 exec, exec, s[6:7]
	v_or_b32_e32 v0, 0x580, v2
	v_cmp_lt_u32_e32 vcc, v0, v244
	v_mov_b32_e32 v28, 0
	v_mov_b32_e32 v29, 0
	s_and_saveexec_b64 s[6:7], vcc
	s_cbranch_execz .LBB0_765
	v_or_b32_e32 v0, 0x580, v2
	v_lshlrev_b32_e32 v0, 2, v0
	v_lshl_add_u64 v[30:31], v[230:231], 0, v[0:1]
	global_load_dword v29, v[30:31], off nt
.LBB0_765:
	s_or_b64 exec, exec, s[6:7]
	v_cmp_lt_u32_e32 vcc, v210, v244
	s_and_saveexec_b64 s[6:7], vcc
	s_cbranch_execz .LBB0_767
	v_lshlrev_b32_e32 v0, 2, v210
	v_lshl_add_u64 v[30:31], v[230:231], 0, v[0:1]
	global_load_dword v28, v[30:31], off nt
; template <int NJ>
; DI void select_row(const float* row, int n, u64* bmrow, int lane) {
;     ...
; #pragma unroll
;   for (int jj = 0; jj < NJ; ++jj) {
;     const int idx = jj * 64 + lane;
;     unsigned k = 0;
;     if (idx < n) { unsigned u = __float_as_uint(__builtin_nontemporal_load(row + idx)); k = (u & 0x80000000u) ? ~u : (u | 0x80000000u); }
;     key[jj] = k;
;   }
.LBB0_767:
	s_or_b64 exec, exec, s[6:7]
	v_or_b32_e32 v0, 0x600, v2
	v_cmp_lt_u32_e32 vcc, v0, v244
	v_mov_b32_e32 v30, 0
	v_mov_b32_e32 v31, 0
	s_and_saveexec_b64 s[6:7], vcc
	s_cbranch_execz .LBB0_769
	v_or_b32_e32 v0, 0x600, v2
	v_lshlrev_b32_e32 v0, 2, v0
	v_lshl_add_u64 v[32:33], v[230:231], 0, v[0:1]
	global_load_dword v31, v[32:33], off nt
.LBB0_769:
	s_or_b64 exec, exec, s[6:7]
	v_or_b32_e32 v0, 0x640, v2
	v_cmp_lt_u32_e32 vcc, v0, v244
	s_and_saveexec_b64 s[6:7], vcc
	s_cbranch_execz .LBB0_771
	v_or_b32_e32 v0, 0x640, v2
	v_lshlrev_b32_e32 v0, 2, v0
	v_lshl_add_u64 v[32:33], v[230:231], 0, v[0:1]
	global_load_dword v30, v[32:33], off nt
.LBB0_771:
	s_or_b64 exec, exec, s[6:7]
	v_cmp_lt_u32_e32 vcc, v204, v244
	v_mov_b32_e32 v32, 0
	v_mov_b32_e32 v33, 0
	s_and_saveexec_b64 s[6:7], vcc
	s_cbranch_execz .LBB0_773
	v_lshlrev_b32_e32 v0, 2, v204
	v_lshl_add_u64 v[34:35], v[230:231], 0, v[0:1]
	global_load_dword v33, v[34:35], off nt
.LBB0_773:
	s_or_b64 exec, exec, s[6:7]
	v_cmp_lt_u32_e32 vcc, v238, v244
	s_and_saveexec_b64 s[6:7], vcc
	s_cbranch_execz .LBB0_775
	v_lshlrev_b32_e32 v0, 2, v238
	v_lshl_add_u64 v[34:35], v[230:231], 0, v[0:1]
	global_load_dword v32, v[34:35], off nt
.LBB0_775:
	s_or_b64 exec, exec, s[6:7]
	v_cmp_lt_u32_e32 vcc, v202, v244
	v_mov_b32_e32 v34, 0
	v_mov_b32_e32 v35, 0
	s_and_saveexec_b64 s[6:7], vcc
	s_cbranch_execz .LBB0_777
	v_lshlrev_b32_e32 v0, 2, v202
	v_lshl_add_u64 v[36:37], v[230:231], 0, v[0:1]
	s_waitcnt vmcnt(48)
	global_load_dword v35, v[36:37], off nt
.LBB0_777:
	s_or_b64 exec, exec, s[6:7]
	v_cmp_lt_u32_e32 vcc, v206, v244
	s_and_saveexec_b64 s[6:7], vcc
	s_cbranch_execz .LBB0_779
	v_lshlrev_b32_e32 v0, 2, v206
	v_lshl_add_u64 v[36:37], v[230:231], 0, v[0:1]
	global_load_dword v34, v[36:37], off nt
.LBB0_779:
	s_or_b64 exec, exec, s[6:7]
	v_cmp_lt_u32_e32 vcc, v208, v244
	v_mov_b32_e32 v36, 0
	v_mov_b32_e32 v37, 0
	s_and_saveexec_b64 s[6:7], vcc
	s_cbranch_execz .LBB0_781
	v_lshlrev_b32_e32 v0, 2, v208
	v_lshl_add_u64 v[212:213], v[230:231], 0, v[0:1]
	global_load_dword v37, v[212:213], off nt
.LBB0_781:
	s_or_b64 exec, exec, s[6:7]
	v_cmp_lt_u32_e32 vcc, v226, v244
	s_and_saveexec_b64 s[6:7], vcc
	s_cbranch_execz .LBB0_783
	v_lshlrev_b32_e32 v0, 2, v226
	v_lshl_add_u64 v[212:213], v[230:231], 0, v[0:1]
	global_load_dword v36, v[212:213], off nt
; DI int shflxi(int v, int m, int lane) { return __builtin_amdgcn_ds_bpermute((lane ^ m) << 2, v); }
; template <int NJ>
; DI void select_row(const float* row, int n, u64* bmrow, int lane) {
;     ...
; #pragma unroll
;   for (int jj = 0; jj < NJ; ++jj) {
;     const int idx = jj * 64 + lane;
;     unsigned k = 0;
;     if (idx < n) { unsigned u = __float_as_uint(__builtin_nontemporal_load(row + idx)); k = (u & 0x80000000u) ? ~u : (u | 0x80000000u); }
;     key[jj] = k;
;   }
;   unsigned km = 0;
; #pragma unroll
;   for (int jj = 0; jj < NJ; ++jj) km = (key[jj] > km) ? key[jj] : km;
; #pragma unroll
;   for (int o = 32; o > 0; o >>= 1) { const unsigned t = (unsigned)shflxi((int)km, o, lane); km = (t > km) ? t : km; }
;   unsigned lo = 0, hi = (km == 0xffffffffu) ? km : (km + 1u), T = 0;
;   bool exact = false;
;   {
;     unsigned cand = km & 0xff800000u;
.LBB0_783:
	s_or_b64 exec, exec, s[6:7]
	s_waitcnt vmcnt(0)
	v_or_b32_e32 v0, 0x100, v2
	v_cmp_lt_u32_e64 s[6:7], v0, v244
	v_not_b32_e32 v0, v6
	v_cmp_gt_i32_e32 vcc, 0, v6
	s_nop 1
	v_cndmask_b32_e64 v0, -|v6|, v0, vcc
	v_cndmask_b32_e64 v6, 0, v0, s[6:7]
	v_or_b32_e32 v0, 0x140, v2
	v_cmp_lt_u32_e64 s[6:7], v0, v244
	v_not_b32_e32 v0, v4
	v_cmp_gt_i32_e32 vcc, 0, v4
	s_nop 1
	v_cndmask_b32_e64 v0, -|v4|, v0, vcc
	v_cndmask_b32_e64 v4, 0, v0, s[6:7]
	v_or_b32_e32 v0, 0x180, v2
	v_cmp_lt_u32_e64 s[6:7], v0, v244
	v_not_b32_e32 v0, v10
	v_cmp_gt_i32_e32 vcc, 0, v10
	s_nop 1
	v_cndmask_b32_e64 v0, -|v10|, v0, vcc
	v_cndmask_b32_e64 v10, 0, v0, s[6:7]
	v_or_b32_e32 v0, 0x1c0, v2
	v_cmp_lt_u32_e64 s[6:7], v0, v244
	v_not_b32_e32 v0, v8
	v_cmp_gt_i32_e32 vcc, 0, v8
	s_nop 1
	v_cndmask_b32_e64 v0, -|v8|, v0, vcc
	v_cndmask_b32_e64 v8, 0, v0, s[6:7]
	v_or_b32_e32 v0, 0x200, v2
	v_cmp_lt_u32_e64 s[6:7], v0, v244
	v_not_b32_e32 v0, v14
	v_cmp_gt_i32_e32 vcc, 0, v14
	s_nop 1
	v_cndmask_b32_e64 v0, -|v14|, v0, vcc
	v_cndmask_b32_e64 v14, 0, v0, s[6:7]
	v_or_b32_e32 v0, 0x240, v2
	v_cmp_lt_u32_e64 s[6:7], v0, v244
	v_not_b32_e32 v0, v12
	v_cmp_gt_i32_e32 vcc, 0, v12
	s_nop 1
	v_cndmask_b32_e64 v0, -|v12|, v0, vcc
	v_cndmask_b32_e64 v12, 0, v0, s[6:7]
	v_or_b32_e32 v0, 0x280, v2
	v_cmp_lt_u32_e64 s[6:7], v0, v244
	v_not_b32_e32 v0, v17
	v_cmp_gt_i32_e32 vcc, 0, v17
	s_nop 1
	v_cndmask_b32_e64 v0, -|v17|, v0, vcc
	v_cndmask_b32_e64 v17, 0, v0, s[6:7]
	v_or_b32_e32 v0, 0x2c0, v2
	v_cmp_lt_u32_e64 s[6:7], v0, v244
	v_not_b32_e32 v0, v16
	v_cmp_gt_i32_e32 vcc, 0, v16
	s_nop 1
	v_cndmask_b32_e64 v0, -|v16|, v0, vcc
	v_cndmask_b32_e64 v16, 0, v0, s[6:7]
	v_or_b32_e32 v0, 0x300, v2
	v_cmp_lt_u32_e64 s[6:7], v0, v244
	v_not_b32_e32 v0, v19
	v_cmp_gt_i32_e32 vcc, 0, v19
	s_nop 1
	v_cndmask_b32_e64 v0, -|v19|, v0, vcc
	v_cndmask_b32_e64 v19, 0, v0, s[6:7]
	v_or_b32_e32 v0, 0x340, v2
	v_cmp_lt_u32_e64 s[6:7], v0, v244
	v_not_b32_e32 v0, v18
	v_cmp_gt_i32_e32 vcc, 0, v18
	s_nop 1
	v_cndmask_b32_e64 v0, -|v18|, v0, vcc
	v_cndmask_b32_e64 v18, 0, v0, s[6:7]
	v_or_b32_e32 v0, 0x380, v2
	v_cmp_lt_u32_e64 s[6:7], v0, v244
	v_not_b32_e32 v0, v21
	v_cmp_gt_i32_e32 vcc, 0, v21
	s_nop 1
	v_cndmask_b32_e64 v0, -|v21|, v0, vcc
	v_cndmask_b32_e64 v21, 0, v0, s[6:7]
	v_or_b32_e32 v0, 0x3c0, v2
	v_cmp_lt_u32_e64 s[6:7], v0, v244
	v_not_b32_e32 v0, v20
	v_cmp_gt_i32_e32 vcc, 0, v20
	s_nop 1
	v_cndmask_b32_e64 v0, -|v20|, v0, vcc
	v_cndmask_b32_e64 v20, 0, v0, s[6:7]
	v_cmp_lt_u32_e64 s[6:7], v196, v244
	v_not_b32_e32 v0, v23
	v_cmp_gt_i32_e32 vcc, 0, v23
	s_nop 1
	v_cndmask_b32_e64 v0, -|v23|, v0, vcc
	v_cndmask_b32_e64 v23, 0, v0, s[6:7]
	v_cmp_lt_u32_e64 s[6:7], v198, v244
	v_not_b32_e32 v0, v22
	v_cmp_gt_i32_e32 vcc, 0, v22
	s_nop 1
	v_cndmask_b32_e64 v0, -|v22|, v0, vcc
	v_cndmask_b32_e64 v22, 0, v0, s[6:7]
	v_cmp_lt_u32_e64 s[6:7], v200, v244
	v_not_b32_e32 v0, v25
	v_cmp_gt_i32_e32 vcc, 0, v25
	s_nop 1
	v_cndmask_b32_e64 v0, -|v25|, v0, vcc
	v_cndmask_b32_e64 v25, 0, v0, s[6:7]
	v_or_b32_e32 v0, 0x4c0, v2
	v_cmp_lt_u32_e64 s[6:7], v0, v244
	v_not_b32_e32 v0, v24
	v_cmp_gt_i32_e32 vcc, 0, v24
	s_nop 1
	v_cndmask_b32_e64 v0, -|v24|, v0, vcc
	v_cndmask_b32_e64 v24, 0, v0, s[6:7]
	v_or_b32_e32 v0, 0x500, v2
	v_cmp_lt_u32_e64 s[6:7], v0, v244
	v_not_b32_e32 v0, v27
	v_cmp_gt_i32_e32 vcc, 0, v27
	s_nop 1
	v_cndmask_b32_e64 v0, -|v27|, v0, vcc
	v_cndmask_b32_e64 v27, 0, v0, s[6:7]
	v_or_b32_e32 v0, 0x540, v2
	v_cmp_lt_u32_e64 s[6:7], v0, v244
	v_not_b32_e32 v0, v26
	v_cmp_gt_i32_e32 vcc, 0, v26
	s_nop 1
	v_cndmask_b32_e64 v0, -|v26|, v0, vcc
	v_cndmask_b32_e64 v26, 0, v0, s[6:7]
	v_or_b32_e32 v0, 0x580, v2
	v_cmp_lt_u32_e64 s[6:7], v0, v244
	v_not_b32_e32 v0, v29
	v_cmp_gt_i32_e32 vcc, 0, v29
	s_nop 1
	v_cndmask_b32_e64 v0, -|v29|, v0, vcc
	v_cndmask_b32_e64 v29, 0, v0, s[6:7]
	v_cmp_lt_u32_e64 s[6:7], v210, v244
	v_not_b32_e32 v0, v28
	v_cmp_gt_i32_e32 vcc, 0, v28
	s_nop 1
	v_cndmask_b32_e64 v0, -|v28|, v0, vcc
	v_cndmask_b32_e64 v28, 0, v0, s[6:7]
	v_or_b32_e32 v0, 0x600, v2
	v_cmp_lt_u32_e64 s[6:7], v0, v244
	v_not_b32_e32 v0, v31
	v_cmp_gt_i32_e32 vcc, 0, v31
	s_nop 1
	v_cndmask_b32_e64 v0, -|v31|, v0, vcc
	v_cndmask_b32_e64 v31, 0, v0, s[6:7]
	v_or_b32_e32 v0, 0x640, v2
	v_cmp_lt_u32_e64 s[6:7], v0, v244
	v_not_b32_e32 v0, v30
	v_cmp_gt_i32_e32 vcc, 0, v30
	s_nop 1
	v_cndmask_b32_e64 v0, -|v30|, v0, vcc
	v_cndmask_b32_e64 v30, 0, v0, s[6:7]
	v_cmp_lt_u32_e64 s[6:7], v204, v244
	v_not_b32_e32 v0, v33
	v_cmp_gt_i32_e32 vcc, 0, v33
	s_nop 1
	v_cndmask_b32_e64 v0, -|v33|, v0, vcc
	v_cndmask_b32_e64 v33, 0, v0, s[6:7]
	v_cmp_lt_u32_e64 s[6:7], v238, v244
	v_not_b32_e32 v0, v32
	v_cmp_gt_i32_e32 vcc, 0, v32
	s_nop 1
	v_cndmask_b32_e64 v0, -|v32|, v0, vcc
	v_cndmask_b32_e64 v32, 0, v0, s[6:7]
	v_cmp_lt_u32_e64 s[6:7], v202, v244
	v_not_b32_e32 v0, v35
	v_cmp_gt_i32_e32 vcc, 0, v35
	s_nop 1
	v_cndmask_b32_e64 v0, -|v35|, v0, vcc
	v_cndmask_b32_e64 v35, 0, v0, s[6:7]
	v_cmp_lt_u32_e64 s[6:7], v206, v244
	v_not_b32_e32 v0, v34
	v_cmp_gt_i32_e32 vcc, 0, v34
	s_nop 1
	v_cndmask_b32_e64 v0, -|v34|, v0, vcc
	v_cndmask_b32_e64 v34, 0, v0, s[6:7]
	v_cmp_lt_u32_e64 s[6:7], v208, v244
	v_not_b32_e32 v0, v37
	v_cmp_gt_i32_e32 vcc, 0, v37
	s_nop 1
	v_cndmask_b32_e64 v0, -|v37|, v0, vcc
	v_cndmask_b32_e64 v37, 0, v0, s[6:7]
	v_cmp_lt_u32_e64 s[6:7], v226, v244
	v_not_b32_e32 v0, v36
	v_cmp_gt_i32_e32 vcc, 0, v36
	s_nop 1
	v_cndmask_b32_e64 v0, -|v36|, v0, vcc
	v_cndmask_b32_e64 v36, 0, v0, s[6:7]
	s_waitcnt vmcnt(0)
	v_not_b32_e32 v0, v43
	v_cmp_gt_i32_e32 vcc, 0, v43
	v_mov_b32_e32 v47, 0
	s_mov_b64 s[26:27], 0
	v_cndmask_b32_e64 v43, -|v43|, v0, vcc
	v_not_b32_e32 v0, v41
	v_cmp_gt_i32_e32 vcc, 0, v41
	s_mov_b64 s[20:21], 0
	v_mov_b32_e32 v49, 3
	v_cndmask_b32_e64 v41, -|v41|, v0, vcc
	v_not_b32_e32 v0, v39
	v_cmp_gt_i32_e32 vcc, 0, v39
	v_max_u32_e32 v38, v41, v43
	s_nop 0
	v_cndmask_b32_e64 v39, -|v39|, v0, vcc
	v_not_b32_e32 v0, v45
	v_cmp_gt_i32_e32 vcc, 0, v45
	s_nop 1
	v_cndmask_b32_e64 v0, -|v45|, v0, vcc
	v_max3_u32 v38, v0, v39, v38
	v_max3_u32 v38, v4, v6, v38
	v_max3_u32 v38, v8, v10, v38
	v_max3_u32 v38, v12, v14, v38
	v_max3_u32 v38, v16, v17, v38
	v_max3_u32 v38, v18, v19, v38
	v_max3_u32 v38, v20, v21, v38
	v_max3_u32 v38, v22, v23, v38
	v_max3_u32 v38, v24, v25, v38
	v_max3_u32 v38, v26, v27, v38
	v_max3_u32 v38, v28, v29, v38
	v_max3_u32 v38, v30, v31, v38
	v_max3_u32 v38, v32, v33, v38
	v_max3_u32 v38, v34, v35, v38
	v_max3_u32 v38, v36, v37, v38
	ds_bpermute_b32 v40, v5, v38
	v_mov_b32_e32 v45, 0
	s_waitcnt lgkmcnt(0)
	v_max_u32_e32 v38, v40, v38
	ds_bpermute_b32 v40, v7, v38
	s_waitcnt lgkmcnt(0)
	v_max_u32_e32 v38, v40, v38
	ds_bpermute_b32 v40, v9, v38
	s_waitcnt lgkmcnt(0)
	v_max_u32_e32 v38, v40, v38
	ds_bpermute_b32 v40, v11, v38
	s_waitcnt lgkmcnt(0)
	v_max_u32_e32 v38, v40, v38
	ds_bpermute_b32 v40, v13, v38
	s_waitcnt lgkmcnt(0)
	v_max_u32_e32 v38, v40, v38
	ds_bpermute_b32 v40, v15, v38
	s_waitcnt lgkmcnt(0)
	v_max_u32_e32 v40, v40, v38
	v_add_u32_e64 v38, v40, 1 clamp
	v_and_b32_e32 v51, 0xff800000, v40
	s_branch .LBB0_787
